# strategy 7.4 static priority raise: waves 4-7 run a copy of both GEMM K-loops with s_setprio levels one higher (load 1 / mfma 2)
# speedup vs baseline: 1.0018x; 1.0018x over previous
; #define PG8_STAGE(bufoff, gbase, voff) do { _Pragma("unroll") for (int _i = 0; _i < 2; ++_i) \
;         __builtin_amdgcn_global_load_lds((const unsigned*)((const char*)(gbase) + (voff)[_i]), (PG8_LAS unsigned*)(lds + (bufoff) + ldsw + _i * 8192), 16, 0, 0); } while (0)
; #define PG8_LDA(dst, b, h) do { _Pragma("unroll") for (int m = 0; m < 4; ++m) _Pragma("unroll") for (int k = 0; k < 2; ++k) dst[m][k] = *(const PG8_LAS bf16x8*)(lds + PG8_SA(b, h) + aoff + m * 2048 + k * 1024); } while (0)
; #define PG8_LDB(dst, b, h) do { _Pragma("unroll") for (int n = 0; n < 2; ++n) _Pragma("unroll") for (int k = 0; k < 2; ++k) dst[n][k] = *(const PG8_LAS bf16x8*)(lds + PG8_SB(b, h) + boff + n * 2048 + k * 1024); } while (0)
; #define PG8_MMA(ai, bj, At, Bt) do { __builtin_amdgcn_s_setprio(1); _Pragma("unroll") for (int m = 0; m < 4; ++m) _Pragma("unroll") for (int n = 0; n < 2; ++n) _Pragma("unroll") for (int k = 0; k < 2; ++k) \
;         acc[ai][bj][m][n] = __builtin_amdgcn_mfma_f32_16x16x32_bf16(Bt[n][k], At[m][k], acc[ai][bj][m][n], 0, 0, 0); __builtin_amdgcn_s_setprio(0); } while (0)
; #define PG8_WAIT_V(n) asm volatile("s_waitcnt vmcnt(" #n ")" ::: "memory")
; template <class Epi, class Sched, bool ALIGN_EPI = false, bool SP2 = false>
; __device__ __forceinline__ void gemm_phase(PG8_LAS unsigned char* lds, const Gemm g, const Sched& S, const Epi& E, int tid_in) {
;     ...
;     f32x4 acc[2][2][4][2];
; #pragma unroll
;     for (int a = 0; a < 2; ++a)
; #pragma unroll
;         for (int b = 0; b < 2; ++b)
; #pragma unroll
;             for (int m = 0; m < 4; ++m)
; #pragma unroll
;                 for (int n = 0; n < 2; ++n) acc[a][b][m][n] = (f32x4){0.f, 0.f, 0.f, 0.f};
;     ...
;         for (int t = 0; t < ntc; t += 2) {
;             const bool last = (t == ntc - 2);
;             const char* a1 = PG8_KA(cA, t + 1);
;             const char* a2 = last ? nA : PG8_KA(cA, t + 2); const char* b2 = last ? nB : cB + (size_t)(t + 2) * kstep;
;             const char* a3 = last ? PG8_KA(nA, 1) : PG8_KA(cA, t + 3); const char* b3 = b2 + kstep;
;             if (last && has_next) S.a_ready(nxt);
;             if constexpr (SP2) {
;             PG8_LDB(B0, 0, 0); PG8_LDB(B1, 0, 1); PG8_SCHED; PG8_LDA(At, 0, 0); PG8_STAGE(PG8_SA(1, 1), a1 + hstepA, voffA);
;             PG8_WAIT_V(8); PG8_WAIT_L(0); PG8_BAR; PG8_MMA(0, 0, At, B0); PG8_MMA(0, 1, At, B1); PG8_BAR; PG8_SCHED;
.LBB0_605:
	s_add_u32 s18, s40, 0x80
	s_addc_u32 s19, s41, 0
	s_add_u32 s20, s10, 0x100
	s_addc_u32 s21, s11, 0
	s_add_u32 s0, s2, 0x80
	s_addc_u32 s1, s3, 0
	s_waitcnt lgkmcnt(0)
	v_lshl_add_u64 v[130:131], s[0:1], 0, v[206:207]
	v_lshl_add_u64 v[132:133], s[0:1], 0, v[208:209]
	s_lshl_b64 s[0:1], s[94:95], 7
	v_mov_b32_e32 v2, 0
	s_add_u32 s22, s0, 0xffffff00
	s_mov_b32 s10, 0
	s_mov_b64 s[0:1], 0
	v_mov_b32_e32 v3, v2
	v_mov_b32_e32 v4, v2
	v_mov_b32_e32 v5, v2
	v_mov_b32_e32 v14, v2
	v_mov_b32_e32 v15, v2
	v_mov_b32_e32 v16, v2
	v_mov_b32_e32 v17, v2
	s_waitcnt vmcnt(0)
	v_mov_b32_e32 v22, v2
	v_mov_b32_e32 v23, v2
	v_mov_b32_e32 v24, v2
	v_mov_b32_e32 v25, v2
	v_mov_b32_e32 v30, v2
	v_mov_b32_e32 v31, v2
	v_mov_b32_e32 v32, v2
	v_mov_b32_e32 v33, v2
	v_mov_b32_e32 v38, v2
	v_mov_b32_e32 v39, v2
	v_mov_b32_e32 v40, v2
	v_mov_b32_e32 v41, v2
	v_mov_b32_e32 v46, v2
	v_mov_b32_e32 v47, v2
	v_mov_b32_e32 v48, v2
	v_mov_b32_e32 v49, v2
	v_mov_b32_e32 v54, v2
	v_mov_b32_e32 v55, v2
	v_mov_b32_e32 v56, v2
	v_mov_b32_e32 v57, v2
	v_mov_b32_e32 v62, v2
	v_mov_b32_e32 v63, v2
	v_mov_b32_e32 v64, v2
	v_mov_b32_e32 v65, v2
	v_mov_b32_e32 v6, v2
	v_mov_b32_e32 v7, v2
	v_mov_b32_e32 v8, v2
	v_mov_b32_e32 v9, v2
	v_mov_b32_e32 v10, v2
	v_mov_b32_e32 v11, v2
	v_mov_b32_e32 v12, v2
	v_mov_b32_e32 v13, v2
	v_mov_b32_e32 v18, v2
	v_mov_b32_e32 v19, v2
	v_mov_b32_e32 v20, v2
	v_mov_b32_e32 v21, v2
	v_mov_b32_e32 v26, v2
	v_mov_b32_e32 v27, v2
	v_mov_b32_e32 v28, v2
	v_mov_b32_e32 v29, v2
	v_mov_b32_e32 v34, v2
	v_mov_b32_e32 v35, v2
	v_mov_b32_e32 v36, v2
	v_mov_b32_e32 v37, v2
	v_mov_b32_e32 v42, v2
	v_mov_b32_e32 v43, v2
	v_mov_b32_e32 v44, v2
	v_mov_b32_e32 v45, v2
	v_mov_b32_e32 v50, v2
	v_mov_b32_e32 v51, v2
	v_mov_b32_e32 v52, v2
	v_mov_b32_e32 v53, v2
	v_mov_b32_e32 v58, v2
	v_mov_b32_e32 v59, v2
	v_mov_b32_e32 v60, v2
	v_mov_b32_e32 v61, v2
	v_mov_b32_e32 v70, v2
	v_mov_b32_e32 v71, v2
	v_mov_b32_e32 v72, v2
	v_mov_b32_e32 v73, v2
	v_mov_b32_e32 v78, v2
	v_mov_b32_e32 v79, v2
	v_mov_b32_e32 v80, v2
	v_mov_b32_e32 v81, v2
	v_mov_b32_e32 v86, v2
	v_mov_b32_e32 v87, v2
	v_mov_b32_e32 v88, v2
	v_mov_b32_e32 v89, v2
	v_mov_b32_e32 v94, v2
	v_mov_b32_e32 v95, v2
	v_mov_b32_e32 v96, v2
	v_mov_b32_e32 v97, v2
	v_mov_b32_e32 v102, v2
	v_mov_b32_e32 v103, v2
	v_mov_b32_e32 v104, v2
	v_mov_b32_e32 v105, v2
	v_mov_b32_e32 v110, v2
	v_mov_b32_e32 v111, v2
	v_mov_b32_e32 v112, v2
	v_mov_b32_e32 v113, v2
	v_mov_b32_e32 v118, v2
	v_mov_b32_e32 v119, v2
	v_mov_b32_e32 v120, v2
	v_mov_b32_e32 v121, v2
	v_mov_b32_e32 v126, v2
	v_mov_b32_e32 v127, v2
	v_mov_b32_e32 v128, v2
	v_mov_b32_e32 v129, v2
	v_mov_b32_e32 v66, v2
	v_mov_b32_e32 v67, v2
	v_mov_b32_e32 v68, v2
	v_mov_b32_e32 v69, v2
	v_mov_b32_e32 v74, v2
	v_mov_b32_e32 v75, v2
	v_mov_b32_e32 v76, v2
	v_mov_b32_e32 v77, v2
	v_mov_b32_e32 v82, v2
	v_mov_b32_e32 v83, v2
	v_mov_b32_e32 v84, v2
	v_mov_b32_e32 v85, v2
	v_mov_b32_e32 v90, v2
	v_mov_b32_e32 v91, v2
	v_mov_b32_e32 v92, v2
	v_mov_b32_e32 v93, v2
	v_mov_b32_e32 v98, v2
	v_mov_b32_e32 v99, v2
	v_mov_b32_e32 v100, v2
	v_mov_b32_e32 v101, v2
	v_mov_b32_e32 v106, v2
	v_mov_b32_e32 v107, v2
	v_mov_b32_e32 v108, v2
	v_mov_b32_e32 v109, v2
	v_mov_b32_e32 v114, v2
	v_mov_b32_e32 v115, v2
	v_mov_b32_e32 v116, v2
	v_mov_b32_e32 v117, v2
	v_mov_b32_e32 v122, v2
	v_mov_b32_e32 v123, v2
	v_mov_b32_e32 v124, v2
	v_mov_b32_e32 v125, v2
	v_readlane_b32 s101, v255, 15
	s_cmp_ge_u32 s101, 4
	s_cbranch_scc1 .Lyk0_loop
.LBB0_606:
	s_or_b32 s11, s10, 1
	s_cmp_ge_u32 s11, s84
	s_cselect_b32 s27, s86, 0
	s_cselect_b32 s79, s85, 0
	s_add_i32 s23, s10, 2
	s_cmp_ge_u32 s23, s84
	s_cselect_b32 s44, s86, 0
	s_cselect_b32 s11, s85, 0
	s_add_u32 s44, s44, s0
	s_addc_u32 s11, s11, s1
	s_add_u32 s44, s2, s44
	s_addc_u32 s11, s3, s11
	s_add_u32 s44, s44, 0x100
	s_addc_u32 s11, s11, 0
	s_add_u32 s46, s20, s0
	s_addc_u32 s47, s21, s1
	s_add_i32 s10, s10, 3
	s_cmp_ge_u32 s10, s84
	s_cselect_b32 s45, s86, 0
	s_cselect_b32 s10, s85, 0
	s_add_u32 s45, s45, s0
	s_addc_u32 s10, s10, s1
	s_add_u32 s45, s2, s45
	s_addc_u32 s10, s3, s10
	s_add_u32 s78, s45, 0x180
	s_addc_u32 s10, s10, 0
	s_cmp_eq_u32 s22, s0
	s_cselect_b32 s45, s41, s11
	s_cselect_b32 s44, s40, s44
	s_cselect_b32 s47, s43, s47
	s_cselect_b32 s46, s42, s46
	s_cselect_b32 s11, s19, s10
	s_cselect_b32 s10, s18, s78
	s_add_i32 s81, 0, 0x10000
	v_add_u32_e32 v0, s81, v205
	s_add_i32 s82, 0, 0x14000
	ds_read_b128 v[134:137], v0
	ds_read_b128 v[138:141], v0 offset:1024
	ds_read_b128 v[142:145], v0 offset:2048
	ds_read_b128 v[146:149], v0 offset:3072
	v_add_u32_e32 v0, s82, v205
	ds_read_b128 v[150:153], v0
	ds_read_b128 v[154:157], v0 offset:1024
	ds_read_b128 v[158:161], v0 offset:2048
	ds_read_b128 v[162:165], v0 offset:3072
	s_add_u32 s78, s27, s0
	s_addc_u32 s79, s79, s1
	v_lshl_add_u64 v[214:215], v[130:131], 0, s[78:79]
	s_add_i32 m0, s58, 0xc000
	ds_read_b128 v[166:169], v246
	ds_read_b128 v[170:173], v246 offset:1024
	ds_read_b128 v[174:177], v246 offset:2048
	ds_read_b128 v[178:181], v246 offset:3072
	ds_read_b128 v[182:185], v246 offset:4096
	ds_read_b128 v[186:189], v246 offset:5120
	ds_read_b128 v[190:193], v246 offset:6144
	ds_read_b128 v[210:213], v246 offset:7168
	global_load_lds_dwordx4 v[214:215], off
	v_lshl_add_u64 v[214:215], v[132:133], 0, s[78:79]
	s_add_i32 m0, s58, 0xe000
	s_nop 0
	global_load_lds_dwordx4 v[214:215], off
	s_waitcnt vmcnt(8)
	s_waitcnt lgkmcnt(0)
	s_barrier
; #define PG8_STAGE(bufoff, gbase, voff) do { _Pragma("unroll") for (int _i = 0; _i < 2; ++_i) \
;         __builtin_amdgcn_global_load_lds((const unsigned*)((const char*)(gbase) + (voff)[_i]), (PG8_LAS unsigned*)(lds + (bufoff) + ldsw + _i * 8192), 16, 0, 0); } while (0)
; #define PG8_LDA(dst, b, h) do { _Pragma("unroll") for (int m = 0; m < 4; ++m) _Pragma("unroll") for (int k = 0; k < 2; ++k) dst[m][k] = *(const PG8_LAS bf16x8*)(lds + PG8_SA(b, h) + aoff + m * 2048 + k * 1024); } while (0)
; #define PG8_MMA(ai, bj, At, Bt) do { __builtin_amdgcn_s_setprio(1); _Pragma("unroll") for (int m = 0; m < 4; ++m) _Pragma("unroll") for (int n = 0; n < 2; ++n) _Pragma("unroll") for (int k = 0; k < 2; ++k) \
;         acc[ai][bj][m][n] = __builtin_amdgcn_mfma_f32_16x16x32_bf16(Bt[n][k], At[m][k], acc[ai][bj][m][n], 0, 0, 0); __builtin_amdgcn_s_setprio(0); } while (0)
; #define PG8_WAIT_V(n) asm volatile("s_waitcnt vmcnt(" #n ")" ::: "memory")
; #define PG8_WAIT_L(n) asm volatile("s_waitcnt lgkmcnt(" #n ")" ::: "memory")
; #define PG8_BAR __builtin_amdgcn_s_barrier()
; #define PG8_SCHED __builtin_amdgcn_sched_barrier(0)
; template <class Epi, class Sched, bool ALIGN_EPI = false, bool SP2 = false>
; __device__ __forceinline__ void gemm_phase(PG8_LAS unsigned char* lds, const Gemm g, const Sched& S, const Epi& E, int tid_in) {
;     ...
;             PG8_WAIT_V(8); PG8_WAIT_L(0); PG8_BAR; PG8_MMA(0, 0, At, B0); PG8_MMA(0, 1, At, B1); PG8_BAR; PG8_SCHED;
;             PG8_LDA(At, 0, 1); PG8_STAGE(PG8_SB(0, 0), b2, voffB); PG8_STAGE(PG8_SB(0, 1), b2 + hstep, voffB); PG8_STAGE(PG8_SA(0, 0), a2, voffA);
;             PG8_WAIT_V(8); PG8_WAIT_L(0); PG8_BAR; PG8_MMA(1, 0, At, B0); PG8_MMA(1, 1, At, B1); PG8_BAR; PG8_SCHED;
	s_setprio 1
	s_waitcnt lgkmcnt(0)
	v_mfma_f32_16x16x32_bf16 v[122:125], v[134:137], v[166:169], v[122:125]
	v_mfma_f32_16x16x32_bf16 v[114:117], v[142:145], v[166:169], v[114:117]
	v_mfma_f32_16x16x32_bf16 v[106:109], v[134:137], v[174:177], v[106:109]
	v_mfma_f32_16x16x32_bf16 v[98:101], v[142:145], v[174:177], v[98:101]
	v_mfma_f32_16x16x32_bf16 v[90:93], v[134:137], v[182:185], v[90:93]
	v_mfma_f32_16x16x32_bf16 v[82:85], v[142:145], v[182:185], v[82:85]
	v_mfma_f32_16x16x32_bf16 v[74:77], v[134:137], v[190:193], v[74:77]
	v_mfma_f32_16x16x32_bf16 v[66:69], v[142:145], v[190:193], v[66:69]
	v_mfma_f32_16x16x32_bf16 v[122:125], v[138:141], v[170:173], v[122:125]
	v_mfma_f32_16x16x32_bf16 v[114:117], v[146:149], v[170:173], v[114:117]
	v_mfma_f32_16x16x32_bf16 v[106:109], v[138:141], v[178:181], v[106:109]
	v_mfma_f32_16x16x32_bf16 v[98:101], v[146:149], v[178:181], v[98:101]
	v_mfma_f32_16x16x32_bf16 v[90:93], v[138:141], v[186:189], v[90:93]
	v_mfma_f32_16x16x32_bf16 v[82:85], v[146:149], v[186:189], v[82:85]
	v_mfma_f32_16x16x32_bf16 v[74:77], v[138:141], v[210:213], v[74:77]
	v_mfma_f32_16x16x32_bf16 v[66:69], v[146:149], v[210:213], v[66:69]
	s_setprio 0
	s_setprio 1
	v_mfma_f32_16x16x32_bf16 v[126:129], v[150:153], v[166:169], v[126:129]
	v_mfma_f32_16x16x32_bf16 v[118:121], v[158:161], v[166:169], v[118:121]
	v_mfma_f32_16x16x32_bf16 v[110:113], v[150:153], v[174:177], v[110:113]
	v_mfma_f32_16x16x32_bf16 v[102:105], v[158:161], v[174:177], v[102:105]
	v_mfma_f32_16x16x32_bf16 v[94:97], v[150:153], v[182:185], v[94:97]
	v_mfma_f32_16x16x32_bf16 v[86:89], v[158:161], v[182:185], v[86:89]
	v_mfma_f32_16x16x32_bf16 v[78:81], v[150:153], v[190:193], v[78:81]
	v_mfma_f32_16x16x32_bf16 v[70:73], v[158:161], v[190:193], v[70:73]
	v_mfma_f32_16x16x32_bf16 v[126:129], v[154:157], v[170:173], v[126:129]
	v_mfma_f32_16x16x32_bf16 v[118:121], v[162:165], v[170:173], v[118:121]
	v_mfma_f32_16x16x32_bf16 v[110:113], v[154:157], v[178:181], v[110:113]
	v_mfma_f32_16x16x32_bf16 v[102:105], v[162:165], v[178:181], v[102:105]
	v_mfma_f32_16x16x32_bf16 v[94:97], v[154:157], v[186:189], v[94:97]
	v_mfma_f32_16x16x32_bf16 v[86:89], v[162:165], v[186:189], v[86:89]
	v_mfma_f32_16x16x32_bf16 v[78:81], v[154:157], v[210:213], v[78:81]
	v_mfma_f32_16x16x32_bf16 v[70:73], v[162:165], v[210:213], v[70:73]
	s_setprio 0
	s_barrier
	s_add_i32 s27, s81, s55
	v_lshl_add_u64 v[214:215], s[46:47], 0, v[202:203]
	s_mov_b32 m0, s27
	ds_read_b128 v[166:169], v246 offset:16384
	ds_read_b128 v[170:173], v246 offset:17408
	ds_read_b128 v[174:177], v246 offset:18432
	ds_read_b128 v[178:181], v246 offset:19456
	ds_read_b128 v[182:185], v246 offset:20480
	ds_read_b128 v[186:189], v246 offset:21504
	ds_read_b128 v[190:193], v246 offset:22528
	ds_read_b128 v[210:213], v246 offset:23552
	global_load_lds_dwordx4 v[214:215], off
	s_add_i32 m0, s27, 0x2000
	v_lshl_add_u64 v[216:217], s[46:47], 0, v[198:199]
	s_add_u32 s46, s46, s52
	s_addc_u32 s47, s47, 0
	s_add_i32 s27, s82, s55
	global_load_lds_dwordx4 v[216:217], off
	v_lshl_add_u64 v[218:219], s[46:47], 0, v[202:203]
	s_mov_b32 m0, s27
	v_lshl_add_u64 v[220:221], s[46:47], 0, v[198:199]
	global_load_lds_dwordx4 v[218:219], off
	s_add_i32 m0, s27, 0x2000
	v_lshl_add_u64 v[234:235], s[44:45], 0, v[200:201]
	global_load_lds_dwordx4 v[220:221], off
	s_mov_b32 m0, s58
	s_nop 0
	global_load_lds_dwordx4 v[234:235], off
	v_lshl_add_u64 v[234:235], s[44:45], 0, v[196:197]
	s_mov_b32 m0, s59
	s_nop 0
	global_load_lds_dwordx4 v[234:235], off
	s_waitcnt vmcnt(8)
	s_waitcnt lgkmcnt(0)
	s_barrier
	s_setprio 1
	s_waitcnt lgkmcnt(0)
	v_mfma_f32_16x16x32_bf16 v[58:61], v[134:137], v[166:169], v[58:61]
	v_mfma_f32_16x16x32_bf16 v[50:53], v[142:145], v[166:169], v[50:53]
	v_mfma_f32_16x16x32_bf16 v[42:45], v[134:137], v[174:177], v[42:45]
	v_mfma_f32_16x16x32_bf16 v[34:37], v[142:145], v[174:177], v[34:37]
	v_mfma_f32_16x16x32_bf16 v[26:29], v[134:137], v[182:185], v[26:29]
	v_mfma_f32_16x16x32_bf16 v[18:21], v[142:145], v[182:185], v[18:21]
	v_mfma_f32_16x16x32_bf16 v[10:13], v[134:137], v[190:193], v[10:13]
	v_mfma_f32_16x16x32_bf16 v[6:9], v[142:145], v[190:193], v[6:9]
	v_mfma_f32_16x16x32_bf16 v[58:61], v[138:141], v[170:173], v[58:61]
	v_mfma_f32_16x16x32_bf16 v[50:53], v[146:149], v[170:173], v[50:53]
	v_mfma_f32_16x16x32_bf16 v[42:45], v[138:141], v[178:181], v[42:45]
	v_mfma_f32_16x16x32_bf16 v[34:37], v[146:149], v[178:181], v[34:37]
	v_mfma_f32_16x16x32_bf16 v[26:29], v[138:141], v[186:189], v[26:29]
	v_mfma_f32_16x16x32_bf16 v[18:21], v[146:149], v[186:189], v[18:21]
	v_mfma_f32_16x16x32_bf16 v[10:13], v[138:141], v[210:213], v[10:13]
	v_mfma_f32_16x16x32_bf16 v[6:9], v[146:149], v[210:213], v[6:9]
	s_setprio 0
	s_setprio 1
	v_mfma_f32_16x16x32_bf16 v[62:65], v[150:153], v[166:169], v[62:65]
	v_mfma_f32_16x16x32_bf16 v[54:57], v[158:161], v[166:169], v[54:57]
	v_mfma_f32_16x16x32_bf16 v[46:49], v[150:153], v[174:177], v[46:49]
	v_mfma_f32_16x16x32_bf16 v[38:41], v[158:161], v[174:177], v[38:41]
	v_mfma_f32_16x16x32_bf16 v[30:33], v[150:153], v[182:185], v[30:33]
	v_mfma_f32_16x16x32_bf16 v[22:25], v[158:161], v[182:185], v[22:25]
	v_mfma_f32_16x16x32_bf16 v[14:17], v[150:153], v[190:193], v[14:17]
	v_mfma_f32_16x16x32_bf16 v[2:5], v[158:161], v[190:193], v[2:5]
	v_mfma_f32_16x16x32_bf16 v[62:65], v[154:157], v[170:173], v[62:65]
	v_mfma_f32_16x16x32_bf16 v[54:57], v[162:165], v[170:173], v[54:57]
	v_mfma_f32_16x16x32_bf16 v[46:49], v[154:157], v[178:181], v[46:49]
	v_mfma_f32_16x16x32_bf16 v[38:41], v[162:165], v[178:181], v[38:41]
	v_mfma_f32_16x16x32_bf16 v[30:33], v[154:157], v[186:189], v[30:33]
	v_mfma_f32_16x16x32_bf16 v[22:25], v[162:165], v[186:189], v[22:25]
	v_mfma_f32_16x16x32_bf16 v[14:17], v[154:157], v[210:213], v[14:17]
	v_mfma_f32_16x16x32_bf16 v[2:5], v[162:165], v[210:213], v[2:5]
	s_setprio 0
	s_barrier
; #define PG8_STAGE(bufoff, gbase, voff) do { _Pragma("unroll") for (int _i = 0; _i < 2; ++_i) \
;         __builtin_amdgcn_global_load_lds((const unsigned*)((const char*)(gbase) + (voff)[_i]), (PG8_LAS unsigned*)(lds + (bufoff) + ldsw + _i * 8192), 16, 0, 0); } while (0)
; #define PG8_LDA(dst, b, h) do { _Pragma("unroll") for (int m = 0; m < 4; ++m) _Pragma("unroll") for (int k = 0; k < 2; ++k) dst[m][k] = *(const PG8_LAS bf16x8*)(lds + PG8_SA(b, h) + aoff + m * 2048 + k * 1024); } while (0)
; #define PG8_LDB(dst, b, h) do { _Pragma("unroll") for (int n = 0; n < 2; ++n) _Pragma("unroll") for (int k = 0; k < 2; ++k) dst[n][k] = *(const PG8_LAS bf16x8*)(lds + PG8_SB(b, h) + boff + n * 2048 + k * 1024); } while (0)
; #define PG8_MMA(ai, bj, At, Bt) do { __builtin_amdgcn_s_setprio(1); _Pragma("unroll") for (int m = 0; m < 4; ++m) _Pragma("unroll") for (int n = 0; n < 2; ++n) _Pragma("unroll") for (int k = 0; k < 2; ++k) \
;         acc[ai][bj][m][n] = __builtin_amdgcn_mfma_f32_16x16x32_bf16(Bt[n][k], At[m][k], acc[ai][bj][m][n], 0, 0, 0); __builtin_amdgcn_s_setprio(0); } while (0)
; #define PG8_WAIT_V(n) asm volatile("s_waitcnt vmcnt(" #n ")" ::: "memory")
; #define PG8_WAIT_L(n) asm volatile("s_waitcnt lgkmcnt(" #n ")" ::: "memory")
; #define PG8_BAR __builtin_amdgcn_s_barrier()
; #define PG8_SCHED __builtin_amdgcn_sched_barrier(0)
; template <class Epi, class Sched, bool ALIGN_EPI = false, bool SP2 = false>
; __device__ __forceinline__ void gemm_phase(PG8_LAS unsigned char* lds, const Gemm g, const Sched& S, const Epi& E, int tid_in) {
;     ...
;             PG8_LDB(B0, 1, 0); PG8_LDB(B1, 1, 1); PG8_SCHED; PG8_LDA(At, 1, 0); PG8_STAGE(PG8_SA(0, 1), a2 + hstepA, voffA);
;             PG8_WAIT_V(8); PG8_WAIT_L(0); PG8_BAR; PG8_MMA(0, 0, At, B0); PG8_MMA(0, 1, At, B1); PG8_BAR; PG8_SCHED;
;             PG8_LDA(At, 1, 1); PG8_STAGE(PG8_SB(1, 0), b3, voffB); PG8_STAGE(PG8_SB(1, 1), b3 + hstep, voffB); PG8_STAGE(PG8_SA(1, 0), a3, voffA);
;             PG8_WAIT_V(8); PG8_WAIT_L(0); PG8_BAR; PG8_MMA(1, 0, At, B0); PG8_MMA(1, 1, At, B1); PG8_BAR; PG8_SCHED;
	s_add_i32 s27, 0, 0x18000
	v_add_u32_e32 v0, s27, v205
	s_add_i32 s46, 0, 0x1c000
	ds_read_b128 v[134:137], v0
	ds_read_b128 v[138:141], v0 offset:1024
	ds_read_b128 v[142:145], v0 offset:2048
	ds_read_b128 v[146:149], v0 offset:3072
	v_add_u32_e32 v0, s46, v205
	ds_read_b128 v[150:153], v0
	ds_read_b128 v[154:157], v0 offset:1024
	ds_read_b128 v[158:161], v0 offset:2048
	ds_read_b128 v[162:165], v0 offset:3072
	s_add_u32 s44, s44, s28
	s_addc_u32 s45, s45, 0
	s_mov_b32 m0, s60
	v_lshl_add_u64 v[234:235], s[44:45], 0, v[200:201]
	ds_read_b128 v[166:169], v246 offset:32768
	ds_read_b128 v[170:173], v246 offset:33792
	ds_read_b128 v[174:177], v246 offset:34816
	ds_read_b128 v[178:181], v246 offset:35840
	ds_read_b128 v[182:185], v246 offset:36864
	ds_read_b128 v[186:189], v246 offset:37888
	ds_read_b128 v[190:193], v246 offset:38912
	ds_read_b128 v[210:213], v246 offset:39936
	global_load_lds_dwordx4 v[234:235], off
	v_lshl_add_u64 v[234:235], s[44:45], 0, v[196:197]
	s_mov_b32 m0, s61
	s_nop 0
	global_load_lds_dwordx4 v[234:235], off
	s_waitcnt vmcnt(8)
	s_waitcnt lgkmcnt(0)
	s_barrier
	s_setprio 1
	s_waitcnt lgkmcnt(0)
	v_mfma_f32_16x16x32_bf16 v[122:125], v[134:137], v[166:169], v[122:125]
	v_mfma_f32_16x16x32_bf16 v[114:117], v[142:145], v[166:169], v[114:117]
	v_mfma_f32_16x16x32_bf16 v[106:109], v[134:137], v[174:177], v[106:109]
	v_mfma_f32_16x16x32_bf16 v[98:101], v[142:145], v[174:177], v[98:101]
	v_mfma_f32_16x16x32_bf16 v[90:93], v[134:137], v[182:185], v[90:93]
	v_mfma_f32_16x16x32_bf16 v[82:85], v[142:145], v[182:185], v[82:85]
	v_mfma_f32_16x16x32_bf16 v[74:77], v[134:137], v[190:193], v[74:77]
	v_mfma_f32_16x16x32_bf16 v[66:69], v[142:145], v[190:193], v[66:69]
	v_mfma_f32_16x16x32_bf16 v[122:125], v[138:141], v[170:173], v[122:125]
	v_mfma_f32_16x16x32_bf16 v[114:117], v[146:149], v[170:173], v[114:117]
	v_mfma_f32_16x16x32_bf16 v[106:109], v[138:141], v[178:181], v[106:109]
	v_mfma_f32_16x16x32_bf16 v[98:101], v[146:149], v[178:181], v[98:101]
	v_mfma_f32_16x16x32_bf16 v[90:93], v[138:141], v[186:189], v[90:93]
	v_mfma_f32_16x16x32_bf16 v[82:85], v[146:149], v[186:189], v[82:85]
	v_mfma_f32_16x16x32_bf16 v[74:77], v[138:141], v[210:213], v[74:77]
	v_mfma_f32_16x16x32_bf16 v[66:69], v[146:149], v[210:213], v[66:69]
	s_setprio 0
	s_setprio 1
	v_mfma_f32_16x16x32_bf16 v[126:129], v[150:153], v[166:169], v[126:129]
	v_mfma_f32_16x16x32_bf16 v[118:121], v[158:161], v[166:169], v[118:121]
	v_mfma_f32_16x16x32_bf16 v[110:113], v[150:153], v[174:177], v[110:113]
	v_mfma_f32_16x16x32_bf16 v[102:105], v[158:161], v[174:177], v[102:105]
	v_mfma_f32_16x16x32_bf16 v[94:97], v[150:153], v[182:185], v[94:97]
	v_mfma_f32_16x16x32_bf16 v[86:89], v[158:161], v[182:185], v[86:89]
	v_mfma_f32_16x16x32_bf16 v[78:81], v[150:153], v[190:193], v[78:81]
	v_mfma_f32_16x16x32_bf16 v[70:73], v[158:161], v[190:193], v[70:73]
	v_mfma_f32_16x16x32_bf16 v[126:129], v[154:157], v[170:173], v[126:129]
	v_mfma_f32_16x16x32_bf16 v[118:121], v[162:165], v[170:173], v[118:121]
	v_mfma_f32_16x16x32_bf16 v[110:113], v[154:157], v[178:181], v[110:113]
	v_mfma_f32_16x16x32_bf16 v[102:105], v[162:165], v[178:181], v[102:105]
	v_mfma_f32_16x16x32_bf16 v[94:97], v[154:157], v[186:189], v[94:97]
	v_mfma_f32_16x16x32_bf16 v[86:89], v[162:165], v[186:189], v[86:89]
	v_mfma_f32_16x16x32_bf16 v[78:81], v[154:157], v[210:213], v[78:81]
	v_mfma_f32_16x16x32_bf16 v[70:73], v[162:165], v[210:213], v[70:73]
	s_setprio 0
	s_barrier
	s_add_i32 s27, s27, s55
	v_lshl_add_u64 v[214:215], v[214:215], 0, s[96:97]
	s_mov_b32 m0, s27
	ds_read_b128 v[166:169], v246 offset:49152
	ds_read_b128 v[170:173], v246 offset:50176
	ds_read_b128 v[174:177], v246 offset:51200
	ds_read_b128 v[178:181], v246 offset:52224
	ds_read_b128 v[182:185], v246 offset:53248
	ds_read_b128 v[186:189], v246 offset:54272
	ds_read_b128 v[190:193], v246 offset:55296
	ds_read_b128 v[210:213], v246 offset:56320
	global_load_lds_dwordx4 v[214:215], off
	v_lshl_add_u64 v[214:215], v[216:217], 0, s[96:97]
	s_add_i32 m0, s27, 0x2000
	s_add_i32 s27, s46, s55
	global_load_lds_dwordx4 v[214:215], off
	v_lshl_add_u64 v[214:215], v[218:219], 0, s[96:97]
	s_mov_b32 m0, s27
	s_nop 0
	global_load_lds_dwordx4 v[214:215], off
	v_lshl_add_u64 v[214:215], v[220:221], 0, s[96:97]
	s_add_i32 m0, s27, 0x2000
	s_nop 0
	global_load_lds_dwordx4 v[214:215], off
	v_lshl_add_u64 v[214:215], s[10:11], 0, v[200:201]
	s_mov_b32 m0, s63
	s_nop 0
	global_load_lds_dwordx4 v[214:215], off
	v_lshl_add_u64 v[214:215], s[10:11], 0, v[196:197]
	s_mov_b32 m0, s64
	s_nop 0
	global_load_lds_dwordx4 v[214:215], off
	s_waitcnt vmcnt(8)
	s_waitcnt lgkmcnt(0)
	s_barrier
	s_setprio 1
	s_waitcnt lgkmcnt(0)
	v_mfma_f32_16x16x32_bf16 v[58:61], v[134:137], v[166:169], v[58:61]
	v_mfma_f32_16x16x32_bf16 v[50:53], v[142:145], v[166:169], v[50:53]
	v_mfma_f32_16x16x32_bf16 v[42:45], v[134:137], v[174:177], v[42:45]
	v_mfma_f32_16x16x32_bf16 v[34:37], v[142:145], v[174:177], v[34:37]
	v_mfma_f32_16x16x32_bf16 v[26:29], v[134:137], v[182:185], v[26:29]
	v_mfma_f32_16x16x32_bf16 v[18:21], v[142:145], v[182:185], v[18:21]
	v_mfma_f32_16x16x32_bf16 v[10:13], v[134:137], v[190:193], v[10:13]
	v_mfma_f32_16x16x32_bf16 v[6:9], v[142:145], v[190:193], v[6:9]
	v_mfma_f32_16x16x32_bf16 v[58:61], v[138:141], v[170:173], v[58:61]
	v_mfma_f32_16x16x32_bf16 v[50:53], v[146:149], v[170:173], v[50:53]
	v_mfma_f32_16x16x32_bf16 v[42:45], v[138:141], v[178:181], v[42:45]
	v_mfma_f32_16x16x32_bf16 v[34:37], v[146:149], v[178:181], v[34:37]
	v_mfma_f32_16x16x32_bf16 v[26:29], v[138:141], v[186:189], v[26:29]
	v_mfma_f32_16x16x32_bf16 v[18:21], v[146:149], v[186:189], v[18:21]
	v_mfma_f32_16x16x32_bf16 v[10:13], v[138:141], v[210:213], v[10:13]
	v_mfma_f32_16x16x32_bf16 v[6:9], v[146:149], v[210:213], v[6:9]
	s_setprio 0
	s_setprio 1
	v_mfma_f32_16x16x32_bf16 v[62:65], v[150:153], v[166:169], v[62:65]
	v_mfma_f32_16x16x32_bf16 v[54:57], v[158:161], v[166:169], v[54:57]
	v_mfma_f32_16x16x32_bf16 v[46:49], v[150:153], v[174:177], v[46:49]
	v_mfma_f32_16x16x32_bf16 v[38:41], v[158:161], v[174:177], v[38:41]
	v_mfma_f32_16x16x32_bf16 v[30:33], v[150:153], v[182:185], v[30:33]
	v_mfma_f32_16x16x32_bf16 v[22:25], v[158:161], v[182:185], v[22:25]
	v_mfma_f32_16x16x32_bf16 v[14:17], v[150:153], v[190:193], v[14:17]
	v_mfma_f32_16x16x32_bf16 v[2:5], v[158:161], v[190:193], v[2:5]
	v_mfma_f32_16x16x32_bf16 v[62:65], v[154:157], v[170:173], v[62:65]
	v_mfma_f32_16x16x32_bf16 v[54:57], v[162:165], v[170:173], v[54:57]
	v_mfma_f32_16x16x32_bf16 v[46:49], v[154:157], v[178:181], v[46:49]
	v_mfma_f32_16x16x32_bf16 v[38:41], v[162:165], v[178:181], v[38:41]
	v_mfma_f32_16x16x32_bf16 v[30:33], v[154:157], v[186:189], v[30:33]
	v_mfma_f32_16x16x32_bf16 v[22:25], v[162:165], v[186:189], v[22:25]
	v_mfma_f32_16x16x32_bf16 v[14:17], v[154:157], v[210:213], v[14:17]
	v_mfma_f32_16x16x32_bf16 v[2:5], v[162:165], v[210:213], v[2:5]
	s_setprio 0
	s_barrier
	s_add_u32 s0, s0, 0x100
	s_addc_u32 s1, s1, 0
	s_cmp_ge_u32 s23, s94
	s_mov_b32 s10, s23
	s_cbranch_scc0 .LBB0_606
	s_branch .Lyk0_exit
; #define PG8_STAGE(bufoff, gbase, voff) do { _Pragma("unroll") for (int _i = 0; _i < 2; ++_i) \
;         __builtin_amdgcn_global_load_lds((const unsigned*)((const char*)(gbase) + (voff)[_i]), (PG8_LAS unsigned*)(lds + (bufoff) + ldsw + _i * 8192), 16, 0, 0); } while (0)
; #define PG8_LDA(dst, b, h) do { _Pragma("unroll") for (int m = 0; m < 4; ++m) _Pragma("unroll") for (int k = 0; k < 2; ++k) dst[m][k] = *(const PG8_LAS bf16x8*)(lds + PG8_SA(b, h) + aoff + m * 2048 + k * 1024); } while (0)
; #define PG8_LDB(dst, b, h) do { _Pragma("unroll") for (int n = 0; n < 2; ++n) _Pragma("unroll") for (int k = 0; k < 2; ++k) dst[n][k] = *(const PG8_LAS bf16x8*)(lds + PG8_SB(b, h) + boff + n * 2048 + k * 1024); } while (0)
; #define PG8_MMA(ai, bj, At, Bt) do { __builtin_amdgcn_s_setprio(1); _Pragma("unroll") for (int m = 0; m < 4; ++m) _Pragma("unroll") for (int n = 0; n < 2; ++n) _Pragma("unroll") for (int k = 0; k < 2; ++k) \
;         acc[ai][bj][m][n] = __builtin_amdgcn_mfma_f32_16x16x32_bf16(Bt[n][k], At[m][k], acc[ai][bj][m][n], 0, 0, 0); __builtin_amdgcn_s_setprio(0); } while (0)
; #define PG8_WAIT_V(n) asm volatile("s_waitcnt vmcnt(" #n ")" ::: "memory")
; #define PG8_WAIT_L(n) asm volatile("s_waitcnt lgkmcnt(" #n ")" ::: "memory")
; #define PG8_BAR __builtin_amdgcn_s_barrier()
; template <class Epi, class Sched, bool ALIGN_EPI = false, bool SP2 = false>
; __device__ __forceinline__ void gemm_phase(PG8_LAS unsigned char* lds, const Gemm g, const Sched& S, const Epi& E, int tid_in) {
;     ...
;         for (int t = 0; t < ntc; t += 2) {
;             const bool last = (t == ntc - 2);
;             const char* a1 = PG8_KA(cA, t + 1);
;             const char* a2 = last ? nA : PG8_KA(cA, t + 2); const char* b2 = last ? nB : cB + (size_t)(t + 2) * kstep;
;             const char* a3 = last ? PG8_KA(nA, 1) : PG8_KA(cA, t + 3); const char* b3 = b2 + kstep;
;             if (last && has_next) S.a_ready(nxt);
;             if constexpr (SP2) {
;             PG8_LDB(B0, 0, 0); PG8_LDB(B1, 0, 1); PG8_SCHED; PG8_LDA(At, 0, 0); PG8_STAGE(PG8_SA(1, 1), a1 + hstepA, voffA);
;             PG8_WAIT_V(8); PG8_WAIT_L(0); PG8_BAR; PG8_MMA(0, 0, At, B0); PG8_MMA(0, 1, At, B1); PG8_BAR; PG8_SCHED;
;             PG8_LDA(At, 0, 1); PG8_STAGE(PG8_SB(0, 0), b2, voffB); PG8_STAGE(PG8_SB(0, 1), b2 + hstep, voffB); PG8_STAGE(PG8_SA(0, 0), a2, voffA);
.Lyk0_loop:
	s_or_b32 s11, s10, 1
	s_cmp_ge_u32 s11, s84
	s_cselect_b32 s27, s86, 0
	s_cselect_b32 s79, s85, 0
	s_add_i32 s23, s10, 2
	s_cmp_ge_u32 s23, s84
	s_cselect_b32 s44, s86, 0
	s_cselect_b32 s11, s85, 0
	s_add_u32 s44, s44, s0
	s_addc_u32 s11, s11, s1
	s_add_u32 s44, s2, s44
	s_addc_u32 s11, s3, s11
	s_add_u32 s44, s44, 0x100
	s_addc_u32 s11, s11, 0
	s_add_u32 s46, s20, s0
	s_addc_u32 s47, s21, s1
	s_add_i32 s10, s10, 3
	s_cmp_ge_u32 s10, s84
	s_cselect_b32 s45, s86, 0
	s_cselect_b32 s10, s85, 0
	s_add_u32 s45, s45, s0
	s_addc_u32 s10, s10, s1
	s_add_u32 s45, s2, s45
	s_addc_u32 s10, s3, s10
	s_add_u32 s78, s45, 0x180
	s_addc_u32 s10, s10, 0
	s_cmp_eq_u32 s22, s0
	s_cselect_b32 s45, s41, s11
	s_cselect_b32 s44, s40, s44
	s_cselect_b32 s47, s43, s47
	s_cselect_b32 s46, s42, s46
	s_cselect_b32 s11, s19, s10
	s_cselect_b32 s10, s18, s78
	s_add_i32 s81, 0, 0x10000
	v_add_u32_e32 v0, s81, v205
	s_add_i32 s82, 0, 0x14000
	ds_read_b128 v[134:137], v0
	ds_read_b128 v[138:141], v0 offset:1024
	ds_read_b128 v[142:145], v0 offset:2048
	ds_read_b128 v[146:149], v0 offset:3072
	v_add_u32_e32 v0, s82, v205
	ds_read_b128 v[150:153], v0
	ds_read_b128 v[154:157], v0 offset:1024
	ds_read_b128 v[158:161], v0 offset:2048
	ds_read_b128 v[162:165], v0 offset:3072
	s_add_u32 s78, s27, s0
	s_addc_u32 s79, s79, s1
	v_lshl_add_u64 v[214:215], v[130:131], 0, s[78:79]
	s_add_i32 m0, s58, 0xc000
	ds_read_b128 v[166:169], v246
	ds_read_b128 v[170:173], v246 offset:1024
	ds_read_b128 v[174:177], v246 offset:2048
	ds_read_b128 v[178:181], v246 offset:3072
	ds_read_b128 v[182:185], v246 offset:4096
	ds_read_b128 v[186:189], v246 offset:5120
	ds_read_b128 v[190:193], v246 offset:6144
	ds_read_b128 v[210:213], v246 offset:7168
	global_load_lds_dwordx4 v[214:215], off
	v_lshl_add_u64 v[214:215], v[132:133], 0, s[78:79]
	s_add_i32 m0, s58, 0xe000
	s_nop 0
	global_load_lds_dwordx4 v[214:215], off
	s_waitcnt vmcnt(8)
	s_waitcnt lgkmcnt(0)
	s_barrier
	s_setprio 2
	s_waitcnt lgkmcnt(0)
	v_mfma_f32_16x16x32_bf16 v[122:125], v[134:137], v[166:169], v[122:125]
	v_mfma_f32_16x16x32_bf16 v[114:117], v[142:145], v[166:169], v[114:117]
	v_mfma_f32_16x16x32_bf16 v[106:109], v[134:137], v[174:177], v[106:109]
	v_mfma_f32_16x16x32_bf16 v[98:101], v[142:145], v[174:177], v[98:101]
	v_mfma_f32_16x16x32_bf16 v[90:93], v[134:137], v[182:185], v[90:93]
	v_mfma_f32_16x16x32_bf16 v[82:85], v[142:145], v[182:185], v[82:85]
	v_mfma_f32_16x16x32_bf16 v[74:77], v[134:137], v[190:193], v[74:77]
	v_mfma_f32_16x16x32_bf16 v[66:69], v[142:145], v[190:193], v[66:69]
	v_mfma_f32_16x16x32_bf16 v[122:125], v[138:141], v[170:173], v[122:125]
	v_mfma_f32_16x16x32_bf16 v[114:117], v[146:149], v[170:173], v[114:117]
	v_mfma_f32_16x16x32_bf16 v[106:109], v[138:141], v[178:181], v[106:109]
	v_mfma_f32_16x16x32_bf16 v[98:101], v[146:149], v[178:181], v[98:101]
	v_mfma_f32_16x16x32_bf16 v[90:93], v[138:141], v[186:189], v[90:93]
	v_mfma_f32_16x16x32_bf16 v[82:85], v[146:149], v[186:189], v[82:85]
	v_mfma_f32_16x16x32_bf16 v[74:77], v[138:141], v[210:213], v[74:77]
	v_mfma_f32_16x16x32_bf16 v[66:69], v[146:149], v[210:213], v[66:69]
	s_setprio 1
	s_setprio 2
	v_mfma_f32_16x16x32_bf16 v[126:129], v[150:153], v[166:169], v[126:129]
	v_mfma_f32_16x16x32_bf16 v[118:121], v[158:161], v[166:169], v[118:121]
	v_mfma_f32_16x16x32_bf16 v[110:113], v[150:153], v[174:177], v[110:113]
	v_mfma_f32_16x16x32_bf16 v[102:105], v[158:161], v[174:177], v[102:105]
	v_mfma_f32_16x16x32_bf16 v[94:97], v[150:153], v[182:185], v[94:97]
	v_mfma_f32_16x16x32_bf16 v[86:89], v[158:161], v[182:185], v[86:89]
	v_mfma_f32_16x16x32_bf16 v[78:81], v[150:153], v[190:193], v[78:81]
	v_mfma_f32_16x16x32_bf16 v[70:73], v[158:161], v[190:193], v[70:73]
	v_mfma_f32_16x16x32_bf16 v[126:129], v[154:157], v[170:173], v[126:129]
	v_mfma_f32_16x16x32_bf16 v[118:121], v[162:165], v[170:173], v[118:121]
	v_mfma_f32_16x16x32_bf16 v[110:113], v[154:157], v[178:181], v[110:113]
	v_mfma_f32_16x16x32_bf16 v[102:105], v[162:165], v[178:181], v[102:105]
	v_mfma_f32_16x16x32_bf16 v[94:97], v[154:157], v[186:189], v[94:97]
	v_mfma_f32_16x16x32_bf16 v[86:89], v[162:165], v[186:189], v[86:89]
	v_mfma_f32_16x16x32_bf16 v[78:81], v[154:157], v[210:213], v[78:81]
	v_mfma_f32_16x16x32_bf16 v[70:73], v[162:165], v[210:213], v[70:73]
	s_setprio 1
	s_barrier
	s_add_i32 s27, s81, s55
	v_lshl_add_u64 v[214:215], s[46:47], 0, v[202:203]
	s_mov_b32 m0, s27
	ds_read_b128 v[166:169], v246 offset:16384
	ds_read_b128 v[170:173], v246 offset:17408
	ds_read_b128 v[174:177], v246 offset:18432
	ds_read_b128 v[178:181], v246 offset:19456
	ds_read_b128 v[182:185], v246 offset:20480
	ds_read_b128 v[186:189], v246 offset:21504
	ds_read_b128 v[190:193], v246 offset:22528
	ds_read_b128 v[210:213], v246 offset:23552
	global_load_lds_dwordx4 v[214:215], off
	s_add_i32 m0, s27, 0x2000
	v_lshl_add_u64 v[216:217], s[46:47], 0, v[198:199]
	s_add_u32 s46, s46, s52
	s_addc_u32 s47, s47, 0
	s_add_i32 s27, s82, s55
	global_load_lds_dwordx4 v[216:217], off
	v_lshl_add_u64 v[218:219], s[46:47], 0, v[202:203]
	s_mov_b32 m0, s27
	v_lshl_add_u64 v[220:221], s[46:47], 0, v[198:199]
	global_load_lds_dwordx4 v[218:219], off
	s_add_i32 m0, s27, 0x2000
	v_lshl_add_u64 v[234:235], s[44:45], 0, v[200:201]
	global_load_lds_dwordx4 v[220:221], off
	s_mov_b32 m0, s58
	s_nop 0
	global_load_lds_dwordx4 v[234:235], off
	v_lshl_add_u64 v[234:235], s[44:45], 0, v[196:197]
	s_mov_b32 m0, s59
	s_nop 0
	global_load_lds_dwordx4 v[234:235], off
	s_waitcnt vmcnt(8)
	s_waitcnt lgkmcnt(0)
	s_barrier
; #define PG8_STAGE(bufoff, gbase, voff) do { _Pragma("unroll") for (int _i = 0; _i < 2; ++_i) \
;         __builtin_amdgcn_global_load_lds((const unsigned*)((const char*)(gbase) + (voff)[_i]), (PG8_LAS unsigned*)(lds + (bufoff) + ldsw + _i * 8192), 16, 0, 0); } while (0)
; #define PG8_LDA(dst, b, h) do { _Pragma("unroll") for (int m = 0; m < 4; ++m) _Pragma("unroll") for (int k = 0; k < 2; ++k) dst[m][k] = *(const PG8_LAS bf16x8*)(lds + PG8_SA(b, h) + aoff + m * 2048 + k * 1024); } while (0)
; #define PG8_LDB(dst, b, h) do { _Pragma("unroll") for (int n = 0; n < 2; ++n) _Pragma("unroll") for (int k = 0; k < 2; ++k) dst[n][k] = *(const PG8_LAS bf16x8*)(lds + PG8_SB(b, h) + boff + n * 2048 + k * 1024); } while (0)
; #define PG8_MMA(ai, bj, At, Bt) do { __builtin_amdgcn_s_setprio(1); _Pragma("unroll") for (int m = 0; m < 4; ++m) _Pragma("unroll") for (int n = 0; n < 2; ++n) _Pragma("unroll") for (int k = 0; k < 2; ++k) \
;         acc[ai][bj][m][n] = __builtin_amdgcn_mfma_f32_16x16x32_bf16(Bt[n][k], At[m][k], acc[ai][bj][m][n], 0, 0, 0); __builtin_amdgcn_s_setprio(0); } while (0)
; #define PG8_WAIT_V(n) asm volatile("s_waitcnt vmcnt(" #n ")" ::: "memory")
; #define PG8_WAIT_L(n) asm volatile("s_waitcnt lgkmcnt(" #n ")" ::: "memory")
; #define PG8_BAR __builtin_amdgcn_s_barrier()
; #define PG8_SCHED __builtin_amdgcn_sched_barrier(0)
; template <class Epi, class Sched, bool ALIGN_EPI = false, bool SP2 = false>
; __device__ __forceinline__ void gemm_phase(PG8_LAS unsigned char* lds, const Gemm g, const Sched& S, const Epi& E, int tid_in) {
;     ...
;             PG8_WAIT_V(8); PG8_WAIT_L(0); PG8_BAR; PG8_MMA(1, 0, At, B0); PG8_MMA(1, 1, At, B1); PG8_BAR; PG8_SCHED;
;             PG8_LDB(B0, 1, 0); PG8_LDB(B1, 1, 1); PG8_SCHED; PG8_LDA(At, 1, 0); PG8_STAGE(PG8_SA(0, 1), a2 + hstepA, voffA);
;             PG8_WAIT_V(8); PG8_WAIT_L(0); PG8_BAR; PG8_MMA(0, 0, At, B0); PG8_MMA(0, 1, At, B1); PG8_BAR; PG8_SCHED;
;             PG8_LDA(At, 1, 1); PG8_STAGE(PG8_SB(1, 0), b3, voffB); PG8_STAGE(PG8_SB(1, 1), b3 + hstep, voffB); PG8_STAGE(PG8_SA(1, 0), a3, voffA);
	s_setprio 2
	s_waitcnt lgkmcnt(0)
	v_mfma_f32_16x16x32_bf16 v[58:61], v[134:137], v[166:169], v[58:61]
	v_mfma_f32_16x16x32_bf16 v[50:53], v[142:145], v[166:169], v[50:53]
	v_mfma_f32_16x16x32_bf16 v[42:45], v[134:137], v[174:177], v[42:45]
	v_mfma_f32_16x16x32_bf16 v[34:37], v[142:145], v[174:177], v[34:37]
	v_mfma_f32_16x16x32_bf16 v[26:29], v[134:137], v[182:185], v[26:29]
	v_mfma_f32_16x16x32_bf16 v[18:21], v[142:145], v[182:185], v[18:21]
	v_mfma_f32_16x16x32_bf16 v[10:13], v[134:137], v[190:193], v[10:13]
	v_mfma_f32_16x16x32_bf16 v[6:9], v[142:145], v[190:193], v[6:9]
	v_mfma_f32_16x16x32_bf16 v[58:61], v[138:141], v[170:173], v[58:61]
	v_mfma_f32_16x16x32_bf16 v[50:53], v[146:149], v[170:173], v[50:53]
	v_mfma_f32_16x16x32_bf16 v[42:45], v[138:141], v[178:181], v[42:45]
	v_mfma_f32_16x16x32_bf16 v[34:37], v[146:149], v[178:181], v[34:37]
	v_mfma_f32_16x16x32_bf16 v[26:29], v[138:141], v[186:189], v[26:29]
	v_mfma_f32_16x16x32_bf16 v[18:21], v[146:149], v[186:189], v[18:21]
	v_mfma_f32_16x16x32_bf16 v[10:13], v[138:141], v[210:213], v[10:13]
	v_mfma_f32_16x16x32_bf16 v[6:9], v[146:149], v[210:213], v[6:9]
	s_setprio 1
	s_setprio 2
	v_mfma_f32_16x16x32_bf16 v[62:65], v[150:153], v[166:169], v[62:65]
	v_mfma_f32_16x16x32_bf16 v[54:57], v[158:161], v[166:169], v[54:57]
	v_mfma_f32_16x16x32_bf16 v[46:49], v[150:153], v[174:177], v[46:49]
	v_mfma_f32_16x16x32_bf16 v[38:41], v[158:161], v[174:177], v[38:41]
	v_mfma_f32_16x16x32_bf16 v[30:33], v[150:153], v[182:185], v[30:33]
	v_mfma_f32_16x16x32_bf16 v[22:25], v[158:161], v[182:185], v[22:25]
	v_mfma_f32_16x16x32_bf16 v[14:17], v[150:153], v[190:193], v[14:17]
	v_mfma_f32_16x16x32_bf16 v[2:5], v[158:161], v[190:193], v[2:5]
	v_mfma_f32_16x16x32_bf16 v[62:65], v[154:157], v[170:173], v[62:65]
	v_mfma_f32_16x16x32_bf16 v[54:57], v[162:165], v[170:173], v[54:57]
	v_mfma_f32_16x16x32_bf16 v[46:49], v[154:157], v[178:181], v[46:49]
	v_mfma_f32_16x16x32_bf16 v[38:41], v[162:165], v[178:181], v[38:41]
	v_mfma_f32_16x16x32_bf16 v[30:33], v[154:157], v[186:189], v[30:33]
	v_mfma_f32_16x16x32_bf16 v[22:25], v[162:165], v[186:189], v[22:25]
	v_mfma_f32_16x16x32_bf16 v[14:17], v[154:157], v[210:213], v[14:17]
	v_mfma_f32_16x16x32_bf16 v[2:5], v[162:165], v[210:213], v[2:5]
	s_setprio 1
	s_barrier
	s_add_i32 s27, 0, 0x18000
	v_add_u32_e32 v0, s27, v205
	s_add_i32 s46, 0, 0x1c000
	ds_read_b128 v[134:137], v0
	ds_read_b128 v[138:141], v0 offset:1024
	ds_read_b128 v[142:145], v0 offset:2048
	ds_read_b128 v[146:149], v0 offset:3072
	v_add_u32_e32 v0, s46, v205
	ds_read_b128 v[150:153], v0
	ds_read_b128 v[154:157], v0 offset:1024
	ds_read_b128 v[158:161], v0 offset:2048
	ds_read_b128 v[162:165], v0 offset:3072
	s_add_u32 s44, s44, s28
	s_addc_u32 s45, s45, 0
	s_mov_b32 m0, s60
	v_lshl_add_u64 v[234:235], s[44:45], 0, v[200:201]
	ds_read_b128 v[166:169], v246 offset:32768
	ds_read_b128 v[170:173], v246 offset:33792
	ds_read_b128 v[174:177], v246 offset:34816
	ds_read_b128 v[178:181], v246 offset:35840
	ds_read_b128 v[182:185], v246 offset:36864
	ds_read_b128 v[186:189], v246 offset:37888
	ds_read_b128 v[190:193], v246 offset:38912
	ds_read_b128 v[210:213], v246 offset:39936
	global_load_lds_dwordx4 v[234:235], off
	v_lshl_add_u64 v[234:235], s[44:45], 0, v[196:197]
	s_mov_b32 m0, s61
	s_nop 0
	global_load_lds_dwordx4 v[234:235], off
	s_waitcnt vmcnt(8)
	s_waitcnt lgkmcnt(0)
	s_barrier
	s_setprio 2
	s_waitcnt lgkmcnt(0)
	v_mfma_f32_16x16x32_bf16 v[122:125], v[134:137], v[166:169], v[122:125]
	v_mfma_f32_16x16x32_bf16 v[114:117], v[142:145], v[166:169], v[114:117]
	v_mfma_f32_16x16x32_bf16 v[106:109], v[134:137], v[174:177], v[106:109]
	v_mfma_f32_16x16x32_bf16 v[98:101], v[142:145], v[174:177], v[98:101]
	v_mfma_f32_16x16x32_bf16 v[90:93], v[134:137], v[182:185], v[90:93]
	v_mfma_f32_16x16x32_bf16 v[82:85], v[142:145], v[182:185], v[82:85]
	v_mfma_f32_16x16x32_bf16 v[74:77], v[134:137], v[190:193], v[74:77]
	v_mfma_f32_16x16x32_bf16 v[66:69], v[142:145], v[190:193], v[66:69]
	v_mfma_f32_16x16x32_bf16 v[122:125], v[138:141], v[170:173], v[122:125]
	v_mfma_f32_16x16x32_bf16 v[114:117], v[146:149], v[170:173], v[114:117]
	v_mfma_f32_16x16x32_bf16 v[106:109], v[138:141], v[178:181], v[106:109]
	v_mfma_f32_16x16x32_bf16 v[98:101], v[146:149], v[178:181], v[98:101]
	v_mfma_f32_16x16x32_bf16 v[90:93], v[138:141], v[186:189], v[90:93]
	v_mfma_f32_16x16x32_bf16 v[82:85], v[146:149], v[186:189], v[82:85]
	v_mfma_f32_16x16x32_bf16 v[74:77], v[138:141], v[210:213], v[74:77]
	v_mfma_f32_16x16x32_bf16 v[66:69], v[146:149], v[210:213], v[66:69]
	s_setprio 1
	s_setprio 2
	v_mfma_f32_16x16x32_bf16 v[126:129], v[150:153], v[166:169], v[126:129]
	v_mfma_f32_16x16x32_bf16 v[118:121], v[158:161], v[166:169], v[118:121]
	v_mfma_f32_16x16x32_bf16 v[110:113], v[150:153], v[174:177], v[110:113]
	v_mfma_f32_16x16x32_bf16 v[102:105], v[158:161], v[174:177], v[102:105]
	v_mfma_f32_16x16x32_bf16 v[94:97], v[150:153], v[182:185], v[94:97]
	v_mfma_f32_16x16x32_bf16 v[86:89], v[158:161], v[182:185], v[86:89]
	v_mfma_f32_16x16x32_bf16 v[78:81], v[150:153], v[190:193], v[78:81]
	v_mfma_f32_16x16x32_bf16 v[70:73], v[158:161], v[190:193], v[70:73]
	v_mfma_f32_16x16x32_bf16 v[126:129], v[154:157], v[170:173], v[126:129]
	v_mfma_f32_16x16x32_bf16 v[118:121], v[162:165], v[170:173], v[118:121]
	v_mfma_f32_16x16x32_bf16 v[110:113], v[154:157], v[178:181], v[110:113]
	v_mfma_f32_16x16x32_bf16 v[102:105], v[162:165], v[178:181], v[102:105]
	v_mfma_f32_16x16x32_bf16 v[94:97], v[154:157], v[186:189], v[94:97]
	v_mfma_f32_16x16x32_bf16 v[86:89], v[162:165], v[186:189], v[86:89]
	v_mfma_f32_16x16x32_bf16 v[78:81], v[154:157], v[210:213], v[78:81]
	v_mfma_f32_16x16x32_bf16 v[70:73], v[162:165], v[210:213], v[70:73]
	s_setprio 1
	s_barrier
; #define PG8_STAGE(bufoff, gbase, voff) do { _Pragma("unroll") for (int _i = 0; _i < 2; ++_i) \
;         __builtin_amdgcn_global_load_lds((const unsigned*)((const char*)(gbase) + (voff)[_i]), (PG8_LAS unsigned*)(lds + (bufoff) + ldsw + _i * 8192), 16, 0, 0); } while (0)
; #define PG8_LDA(dst, b, h) do { _Pragma("unroll") for (int m = 0; m < 4; ++m) _Pragma("unroll") for (int k = 0; k < 2; ++k) dst[m][k] = *(const PG8_LAS bf16x8*)(lds + PG8_SA(b, h) + aoff + m * 2048 + k * 1024); } while (0)
; #define PG8_MMA(ai, bj, At, Bt) do { __builtin_amdgcn_s_setprio(1); _Pragma("unroll") for (int m = 0; m < 4; ++m) _Pragma("unroll") for (int n = 0; n < 2; ++n) _Pragma("unroll") for (int k = 0; k < 2; ++k) \
;         acc[ai][bj][m][n] = __builtin_amdgcn_mfma_f32_16x16x32_bf16(Bt[n][k], At[m][k], acc[ai][bj][m][n], 0, 0, 0); __builtin_amdgcn_s_setprio(0); } while (0)
; #define PG8_WAIT_V(n) asm volatile("s_waitcnt vmcnt(" #n ")" ::: "memory")
; #define PG8_WAIT_L(n) asm volatile("s_waitcnt lgkmcnt(" #n ")" ::: "memory")
; #define PG8_BAR __builtin_amdgcn_s_barrier()
; #define PG8_SCHED __builtin_amdgcn_sched_barrier(0)
; template <class Epi, class Sched, bool ALIGN_EPI = false, bool SP2 = false>
; __device__ __forceinline__ void gemm_phase(PG8_LAS unsigned char* lds, const Gemm g, const Sched& S, const Epi& E, int tid_in) {
;     ...
;             PG8_LDA(At, 1, 1); PG8_STAGE(PG8_SB(1, 0), b3, voffB); PG8_STAGE(PG8_SB(1, 1), b3 + hstep, voffB); PG8_STAGE(PG8_SA(1, 0), a3, voffA);
;             PG8_WAIT_V(8); PG8_WAIT_L(0); PG8_BAR; PG8_MMA(1, 0, At, B0); PG8_MMA(1, 1, At, B1); PG8_BAR; PG8_SCHED;
	s_add_i32 s27, s27, s55
	v_lshl_add_u64 v[214:215], v[214:215], 0, s[96:97]
	s_mov_b32 m0, s27
	ds_read_b128 v[166:169], v246 offset:49152
	ds_read_b128 v[170:173], v246 offset:50176
	ds_read_b128 v[174:177], v246 offset:51200
	ds_read_b128 v[178:181], v246 offset:52224
	ds_read_b128 v[182:185], v246 offset:53248
	ds_read_b128 v[186:189], v246 offset:54272
	ds_read_b128 v[190:193], v246 offset:55296
	ds_read_b128 v[210:213], v246 offset:56320
	global_load_lds_dwordx4 v[214:215], off
	v_lshl_add_u64 v[214:215], v[216:217], 0, s[96:97]
	s_add_i32 m0, s27, 0x2000
	s_add_i32 s27, s46, s55
	global_load_lds_dwordx4 v[214:215], off
	v_lshl_add_u64 v[214:215], v[218:219], 0, s[96:97]
	s_mov_b32 m0, s27
	s_nop 0
	global_load_lds_dwordx4 v[214:215], off
	v_lshl_add_u64 v[214:215], v[220:221], 0, s[96:97]
	s_add_i32 m0, s27, 0x2000
	s_nop 0
	global_load_lds_dwordx4 v[214:215], off
	v_lshl_add_u64 v[214:215], s[10:11], 0, v[200:201]
	s_mov_b32 m0, s63
	s_nop 0
	global_load_lds_dwordx4 v[214:215], off
	v_lshl_add_u64 v[214:215], s[10:11], 0, v[196:197]
	s_mov_b32 m0, s64
	s_nop 0
	global_load_lds_dwordx4 v[214:215], off
	s_waitcnt vmcnt(8)
	s_waitcnt lgkmcnt(0)
	s_barrier
	s_setprio 2
	s_waitcnt lgkmcnt(0)
	v_mfma_f32_16x16x32_bf16 v[58:61], v[134:137], v[166:169], v[58:61]
	v_mfma_f32_16x16x32_bf16 v[50:53], v[142:145], v[166:169], v[50:53]
	v_mfma_f32_16x16x32_bf16 v[42:45], v[134:137], v[174:177], v[42:45]
	v_mfma_f32_16x16x32_bf16 v[34:37], v[142:145], v[174:177], v[34:37]
	v_mfma_f32_16x16x32_bf16 v[26:29], v[134:137], v[182:185], v[26:29]
	v_mfma_f32_16x16x32_bf16 v[18:21], v[142:145], v[182:185], v[18:21]
	v_mfma_f32_16x16x32_bf16 v[10:13], v[134:137], v[190:193], v[10:13]
	v_mfma_f32_16x16x32_bf16 v[6:9], v[142:145], v[190:193], v[6:9]
	v_mfma_f32_16x16x32_bf16 v[58:61], v[138:141], v[170:173], v[58:61]
	v_mfma_f32_16x16x32_bf16 v[50:53], v[146:149], v[170:173], v[50:53]
	v_mfma_f32_16x16x32_bf16 v[42:45], v[138:141], v[178:181], v[42:45]
	v_mfma_f32_16x16x32_bf16 v[34:37], v[146:149], v[178:181], v[34:37]
	v_mfma_f32_16x16x32_bf16 v[26:29], v[138:141], v[186:189], v[26:29]
	v_mfma_f32_16x16x32_bf16 v[18:21], v[146:149], v[186:189], v[18:21]
	v_mfma_f32_16x16x32_bf16 v[10:13], v[138:141], v[210:213], v[10:13]
	v_mfma_f32_16x16x32_bf16 v[6:9], v[146:149], v[210:213], v[6:9]
	s_setprio 1
	s_setprio 2
	v_mfma_f32_16x16x32_bf16 v[62:65], v[150:153], v[166:169], v[62:65]
	v_mfma_f32_16x16x32_bf16 v[54:57], v[158:161], v[166:169], v[54:57]
	v_mfma_f32_16x16x32_bf16 v[46:49], v[150:153], v[174:177], v[46:49]
	v_mfma_f32_16x16x32_bf16 v[38:41], v[158:161], v[174:177], v[38:41]
	v_mfma_f32_16x16x32_bf16 v[30:33], v[150:153], v[182:185], v[30:33]
	v_mfma_f32_16x16x32_bf16 v[22:25], v[158:161], v[182:185], v[22:25]
	v_mfma_f32_16x16x32_bf16 v[14:17], v[150:153], v[190:193], v[14:17]
	v_mfma_f32_16x16x32_bf16 v[2:5], v[158:161], v[190:193], v[2:5]
	v_mfma_f32_16x16x32_bf16 v[62:65], v[154:157], v[170:173], v[62:65]
	v_mfma_f32_16x16x32_bf16 v[54:57], v[162:165], v[170:173], v[54:57]
	v_mfma_f32_16x16x32_bf16 v[46:49], v[154:157], v[178:181], v[46:49]
	v_mfma_f32_16x16x32_bf16 v[38:41], v[162:165], v[178:181], v[38:41]
	v_mfma_f32_16x16x32_bf16 v[30:33], v[154:157], v[186:189], v[30:33]
	v_mfma_f32_16x16x32_bf16 v[22:25], v[162:165], v[186:189], v[22:25]
	v_mfma_f32_16x16x32_bf16 v[14:17], v[154:157], v[210:213], v[14:17]
	v_mfma_f32_16x16x32_bf16 v[2:5], v[162:165], v[210:213], v[2:5]
	s_setprio 1
	s_barrier
	s_add_u32 s0, s0, 0x100
	s_addc_u32 s1, s1, 0
	s_cmp_ge_u32 s23, s94
	s_mov_b32 s10, s23
	s_cbranch_scc0 .Lyk0_loop
	s_setprio 0
.Lyk0_exit:
	v_readlane_b32 s90, v254, 43
	v_readlane_b32 s91, v254, 44
	s_and_b64 vcc, exec, s[34:35]
	s_cbranch_vccz .LBB0_609

; #define PG8_STAGE(bufoff, gbase, voff) do { _Pragma("unroll") for (int _i = 0; _i < 2; ++_i) \
;         __builtin_amdgcn_global_load_lds((const unsigned*)((const char*)(gbase) + (voff)[_i]), (PG8_LAS unsigned*)(lds + (bufoff) + ldsw + _i * 8192), 16, 0, 0); } while (0)
; #define PG8_LDA(dst, b, h) do { _Pragma("unroll") for (int m = 0; m < 4; ++m) _Pragma("unroll") for (int k = 0; k < 2; ++k) dst[m][k] = *(const PG8_LAS bf16x8*)(lds + PG8_SA(b, h) + aoff + m * 2048 + k * 1024); } while (0)
; #define PG8_LDB(dst, b, h) do { _Pragma("unroll") for (int n = 0; n < 2; ++n) _Pragma("unroll") for (int k = 0; k < 2; ++k) dst[n][k] = *(const PG8_LAS bf16x8*)(lds + PG8_SB(b, h) + boff + n * 2048 + k * 1024); } while (0)
; #define PG8_SCHED __builtin_amdgcn_sched_barrier(0)
; template <class Epi, class Sched, bool ALIGN_EPI = false, bool SP2 = false>
; __device__ __forceinline__ void gemm_phase(PG8_LAS unsigned char* lds, const Gemm g, const Sched& S, const Epi& E, int tid_in) {
;     ...
;     f32x4 acc[2][2][4][2];
; #pragma unroll
;     for (int a = 0; a < 2; ++a)
; #pragma unroll
;         for (int b = 0; b < 2; ++b)
; #pragma unroll
;             for (int m = 0; m < 4; ++m)
; #pragma unroll
;                 for (int n = 0; n < 2; ++n) acc[a][b][m][n] = (f32x4){0.f, 0.f, 0.f, 0.f};
;     ...
;         for (int t = 0; t < ntc; t += 2) {
;             const bool last = (t == ntc - 2);
;             const char* a1 = PG8_KA(cA, t + 1);
;             const char* a2 = last ? nA : PG8_KA(cA, t + 2); const char* b2 = last ? nB : cB + (size_t)(t + 2) * kstep;
;             const char* a3 = last ? PG8_KA(nA, 1) : PG8_KA(cA, t + 3); const char* b3 = b2 + kstep;
;             if (last && has_next) S.a_ready(nxt);
;             if constexpr (SP2) {
;             PG8_LDB(B0, 0, 0); PG8_LDB(B1, 0, 1); PG8_SCHED; PG8_LDA(At, 0, 0); PG8_STAGE(PG8_SA(1, 1), a1 + hstepA, voffA);
.LBB0_1179:
	s_add_u32 s21, s48, 0x80
	s_addc_u32 s53, s49, 0
	s_add_u32 s54, s8, 0x100
	v_mov_b32_e32 v8, 0
	s_addc_u32 s55, s9, 0
	s_mov_b32 s0, 0
	s_mov_b32 s56, s79
	v_mov_b32_e32 v9, v8
	v_mov_b32_e32 v10, v8
	v_mov_b32_e32 v11, v8
	v_mov_b32_e32 v16, v8
	v_mov_b32_e32 v17, v8
	v_mov_b32_e32 v18, v8
	v_mov_b32_e32 v19, v8
	v_mov_b32_e32 v24, v8
	v_mov_b32_e32 v25, v8
	v_mov_b32_e32 v26, v8
	v_mov_b32_e32 v27, v8
	v_mov_b32_e32 v32, v8
	v_mov_b32_e32 v33, v8
	v_mov_b32_e32 v34, v8
	v_mov_b32_e32 v35, v8
	v_mov_b32_e32 v40, v8
	v_mov_b32_e32 v41, v8
	v_mov_b32_e32 v42, v8
	v_mov_b32_e32 v43, v8
	v_mov_b32_e32 v48, v8
	v_mov_b32_e32 v49, v8
	v_mov_b32_e32 v50, v8
	v_mov_b32_e32 v51, v8
	v_mov_b32_e32 v56, v8
	v_mov_b32_e32 v57, v8
	v_mov_b32_e32 v58, v8
	v_mov_b32_e32 v59, v8
	v_mov_b32_e32 v64, v8
	v_mov_b32_e32 v65, v8
	v_mov_b32_e32 v66, v8
	v_mov_b32_e32 v67, v8
	v_mov_b32_e32 v4, v8
	v_mov_b32_e32 v5, v8
	v_mov_b32_e32 v6, v8
	v_mov_b32_e32 v7, v8
	v_mov_b32_e32 v12, v8
	v_mov_b32_e32 v13, v8
	v_mov_b32_e32 v14, v8
	v_mov_b32_e32 v15, v8
	v_mov_b32_e32 v20, v8
	v_mov_b32_e32 v21, v8
	v_mov_b32_e32 v22, v8
	v_mov_b32_e32 v23, v8
	v_mov_b32_e32 v28, v8
	v_mov_b32_e32 v29, v8
	v_mov_b32_e32 v30, v8
	v_mov_b32_e32 v31, v8
	v_mov_b32_e32 v36, v8
	v_mov_b32_e32 v37, v8
	v_mov_b32_e32 v38, v8
	v_mov_b32_e32 v39, v8
	v_mov_b32_e32 v44, v8
	v_mov_b32_e32 v45, v8
	v_mov_b32_e32 v46, v8
	v_mov_b32_e32 v47, v8
	v_mov_b32_e32 v52, v8
	v_mov_b32_e32 v53, v8
	v_mov_b32_e32 v54, v8
	v_mov_b32_e32 v55, v8
	v_mov_b32_e32 v60, v8
	v_mov_b32_e32 v61, v8
	v_mov_b32_e32 v62, v8
	v_mov_b32_e32 v63, v8
	v_mov_b32_e32 v72, v8
	v_mov_b32_e32 v73, v8
	v_mov_b32_e32 v74, v8
	v_mov_b32_e32 v75, v8
	v_mov_b32_e32 v80, v8
	v_mov_b32_e32 v81, v8
	v_mov_b32_e32 v82, v8
	v_mov_b32_e32 v83, v8
	v_mov_b32_e32 v88, v8
	v_mov_b32_e32 v89, v8
	v_mov_b32_e32 v90, v8
	v_mov_b32_e32 v91, v8
	v_mov_b32_e32 v96, v8
	v_mov_b32_e32 v97, v8
	v_mov_b32_e32 v98, v8
	v_mov_b32_e32 v99, v8
	v_mov_b32_e32 v104, v8
	v_mov_b32_e32 v105, v8
	v_mov_b32_e32 v106, v8
	v_mov_b32_e32 v107, v8
	v_mov_b32_e32 v112, v8
	v_mov_b32_e32 v113, v8
	v_mov_b32_e32 v114, v8
	v_mov_b32_e32 v115, v8
	v_mov_b32_e32 v120, v8
	v_mov_b32_e32 v121, v8
	v_mov_b32_e32 v122, v8
	v_mov_b32_e32 v123, v8
	v_mov_b32_e32 v128, v8
	v_mov_b32_e32 v129, v8
	v_mov_b32_e32 v130, v8
	v_mov_b32_e32 v131, v8
	v_mov_b32_e32 v68, v8
	v_mov_b32_e32 v69, v8
	v_mov_b32_e32 v70, v8
	v_mov_b32_e32 v71, v8
	v_mov_b32_e32 v76, v8
	v_mov_b32_e32 v77, v8
	v_mov_b32_e32 v78, v8
	v_mov_b32_e32 v79, v8
	v_mov_b32_e32 v84, v8
	v_mov_b32_e32 v85, v8
	v_mov_b32_e32 v86, v8
	v_mov_b32_e32 v87, v8
	v_mov_b32_e32 v92, v8
	v_mov_b32_e32 v93, v8
	v_mov_b32_e32 v94, v8
	v_mov_b32_e32 v95, v8
	v_mov_b32_e32 v100, v8
	v_mov_b32_e32 v101, v8
	v_mov_b32_e32 v102, v8
	v_mov_b32_e32 v103, v8
	v_mov_b32_e32 v108, v8
	v_mov_b32_e32 v109, v8
	v_mov_b32_e32 v110, v8
	v_mov_b32_e32 v111, v8
	v_mov_b32_e32 v116, v8
	v_mov_b32_e32 v117, v8
	v_mov_b32_e32 v118, v8
	v_mov_b32_e32 v119, v8
	v_mov_b32_e32 v124, v8
	v_mov_b32_e32 v125, v8
	v_mov_b32_e32 v126, v8
	v_mov_b32_e32 v127, v8
	s_waitcnt vmcnt(0)
	v_readlane_b32 s101, v255, 15
	s_cmp_ge_u32 s101, 4
	s_cbranch_scc1 .Lyk1_loop
.LBB0_1180:
	s_or_b32 s1, s0, 1
	s_cmp_ge_u32 s1, s84
	s_cselect_b32 s58, s86, 0
	s_cselect_b32 s59, s85, 0
	s_add_i32 s57, s0, 2
	s_cmp_ge_u32 s57, s84
	s_cselect_b32 s8, s86, 0
	s_cselect_b32 s1, s85, 0
	s_add_u32 s8, s6, s8
	s_addc_u32 s1, s7, s1
	s_add_u32 s8, s8, 0x100
	s_addc_u32 s1, s1, 0
	s_add_i32 s0, s0, 3
	s_cmp_ge_u32 s0, s84
	s_cselect_b32 s9, s86, 0
	s_cselect_b32 s0, s85, 0
	s_add_u32 s9, s6, s9
	s_addc_u32 s0, s7, s0
	s_add_u32 s62, s9, 0x180
	s_addc_u32 s0, s0, 0
	s_cmp_eq_u32 s56, 0
	s_cselect_b32 s9, s49, s1
	s_cselect_b32 s8, s48, s8
	s_cselect_b32 s61, s51, s55
	s_cselect_b32 s60, s50, s54
	s_cselect_b32 s1, s53, s0
	s_cselect_b32 s0, s21, s62
	s_add_i32 s62, 0, 0x10000
	v_add_u32_e32 v0, s62, v207
	s_add_i32 s63, 0, 0x14000
	ds_read_b128 v[132:135], v0
	ds_read_b128 v[136:139], v0 offset:1024
	ds_read_b128 v[140:143], v0 offset:2048
	ds_read_b128 v[144:147], v0 offset:3072
	v_add_u32_e32 v0, s63, v207
	ds_read_b128 v[148:151], v0
	ds_read_b128 v[152:155], v0 offset:1024
	ds_read_b128 v[156:159], v0 offset:2048
	ds_read_b128 v[160:163], v0 offset:3072
	v_lshl_add_u64 v[2:3], s[6:7], 0, v[180:181]
	v_lshl_add_u64 v[2:3], v[2:3], 0, s[58:59]
	s_add_i32 m0, s89, 0xc000
	ds_read_b128 v[164:167], v208
	ds_read_b128 v[168:171], v208 offset:1024
	ds_read_b128 v[184:187], v208 offset:2048
	ds_read_b128 v[188:191], v208 offset:3072
	ds_read_b128 v[196:199], v208 offset:4096
	ds_read_b128 v[200:203], v208 offset:5120
	ds_read_b128 v[210:213], v208 offset:6144
	ds_read_b128 v[214:217], v208 offset:7168
	global_load_lds_dwordx4 v[2:3], off
	v_lshl_add_u64 v[2:3], s[6:7], 0, v[182:183]
	v_lshl_add_u64 v[2:3], v[2:3], 0, s[58:59]
	s_add_i32 m0, s89, 0xe000
	s_nop 0
	global_load_lds_dwordx4 v[2:3], off
	s_waitcnt vmcnt(8)
	s_waitcnt lgkmcnt(0)
	s_barrier
; #define PG8_STAGE(bufoff, gbase, voff) do { _Pragma("unroll") for (int _i = 0; _i < 2; ++_i) \
;         __builtin_amdgcn_global_load_lds((const unsigned*)((const char*)(gbase) + (voff)[_i]), (PG8_LAS unsigned*)(lds + (bufoff) + ldsw + _i * 8192), 16, 0, 0); } while (0)
; #define PG8_LDA(dst, b, h) do { _Pragma("unroll") for (int m = 0; m < 4; ++m) _Pragma("unroll") for (int k = 0; k < 2; ++k) dst[m][k] = *(const PG8_LAS bf16x8*)(lds + PG8_SA(b, h) + aoff + m * 2048 + k * 1024); } while (0)
; #define PG8_MMA(ai, bj, At, Bt) do { __builtin_amdgcn_s_setprio(1); _Pragma("unroll") for (int m = 0; m < 4; ++m) _Pragma("unroll") for (int n = 0; n < 2; ++n) _Pragma("unroll") for (int k = 0; k < 2; ++k) \
;         acc[ai][bj][m][n] = __builtin_amdgcn_mfma_f32_16x16x32_bf16(Bt[n][k], At[m][k], acc[ai][bj][m][n], 0, 0, 0); __builtin_amdgcn_s_setprio(0); } while (0)
; #define PG8_WAIT_V(n) asm volatile("s_waitcnt vmcnt(" #n ")" ::: "memory")
; #define PG8_WAIT_L(n) asm volatile("s_waitcnt lgkmcnt(" #n ")" ::: "memory")
; #define PG8_BAR __builtin_amdgcn_s_barrier()
; #define PG8_SCHED __builtin_amdgcn_sched_barrier(0)
; template <class Epi, class Sched, bool ALIGN_EPI = false, bool SP2 = false>
; __device__ __forceinline__ void gemm_phase(PG8_LAS unsigned char* lds, const Gemm g, const Sched& S, const Epi& E, int tid_in) {
;     ...
;             PG8_WAIT_V(8); PG8_WAIT_L(0); PG8_BAR; PG8_MMA(0, 0, At, B0); PG8_MMA(0, 1, At, B1); PG8_BAR; PG8_SCHED;
;             PG8_LDA(At, 0, 1); PG8_STAGE(PG8_SB(0, 0), b2, voffB); PG8_STAGE(PG8_SB(0, 1), b2 + hstep, voffB); PG8_STAGE(PG8_SA(0, 0), a2, voffA);
;             PG8_WAIT_V(8); PG8_WAIT_L(0); PG8_BAR; PG8_MMA(1, 0, At, B0); PG8_MMA(1, 1, At, B1); PG8_BAR; PG8_SCHED;
	s_setprio 1
	s_waitcnt lgkmcnt(0)
	v_mfma_f32_16x16x32_bf16 v[124:127], v[132:135], v[164:167], v[124:127]
	v_mfma_f32_16x16x32_bf16 v[116:119], v[140:143], v[164:167], v[116:119]
	v_mfma_f32_16x16x32_bf16 v[108:111], v[132:135], v[184:187], v[108:111]
	v_mfma_f32_16x16x32_bf16 v[100:103], v[140:143], v[184:187], v[100:103]
	v_mfma_f32_16x16x32_bf16 v[92:95], v[132:135], v[196:199], v[92:95]
	v_mfma_f32_16x16x32_bf16 v[84:87], v[140:143], v[196:199], v[84:87]
	v_mfma_f32_16x16x32_bf16 v[76:79], v[132:135], v[210:213], v[76:79]
	v_mfma_f32_16x16x32_bf16 v[68:71], v[140:143], v[210:213], v[68:71]
	v_mfma_f32_16x16x32_bf16 v[124:127], v[136:139], v[168:171], v[124:127]
	v_mfma_f32_16x16x32_bf16 v[116:119], v[144:147], v[168:171], v[116:119]
	v_mfma_f32_16x16x32_bf16 v[108:111], v[136:139], v[188:191], v[108:111]
	v_mfma_f32_16x16x32_bf16 v[100:103], v[144:147], v[188:191], v[100:103]
	v_mfma_f32_16x16x32_bf16 v[92:95], v[136:139], v[200:203], v[92:95]
	v_mfma_f32_16x16x32_bf16 v[84:87], v[144:147], v[200:203], v[84:87]
	v_mfma_f32_16x16x32_bf16 v[76:79], v[136:139], v[214:217], v[76:79]
	v_mfma_f32_16x16x32_bf16 v[68:71], v[144:147], v[214:217], v[68:71]
	s_setprio 0
	s_setprio 1
	v_mfma_f32_16x16x32_bf16 v[128:131], v[148:151], v[164:167], v[128:131]
	v_mfma_f32_16x16x32_bf16 v[120:123], v[156:159], v[164:167], v[120:123]
	v_mfma_f32_16x16x32_bf16 v[112:115], v[148:151], v[184:187], v[112:115]
	v_mfma_f32_16x16x32_bf16 v[104:107], v[156:159], v[184:187], v[104:107]
	v_mfma_f32_16x16x32_bf16 v[96:99], v[148:151], v[196:199], v[96:99]
	v_mfma_f32_16x16x32_bf16 v[88:91], v[156:159], v[196:199], v[88:91]
	v_mfma_f32_16x16x32_bf16 v[80:83], v[148:151], v[210:213], v[80:83]
	v_mfma_f32_16x16x32_bf16 v[72:75], v[156:159], v[210:213], v[72:75]
	v_mfma_f32_16x16x32_bf16 v[128:131], v[152:155], v[168:171], v[128:131]
	v_mfma_f32_16x16x32_bf16 v[120:123], v[160:163], v[168:171], v[120:123]
	v_mfma_f32_16x16x32_bf16 v[112:115], v[152:155], v[188:191], v[112:115]
	v_mfma_f32_16x16x32_bf16 v[104:107], v[160:163], v[188:191], v[104:107]
	v_mfma_f32_16x16x32_bf16 v[96:99], v[152:155], v[200:203], v[96:99]
	v_mfma_f32_16x16x32_bf16 v[88:91], v[160:163], v[200:203], v[88:91]
	v_mfma_f32_16x16x32_bf16 v[80:83], v[152:155], v[214:217], v[80:83]
	v_mfma_f32_16x16x32_bf16 v[72:75], v[160:163], v[214:217], v[72:75]
	s_setprio 0
	s_barrier
	s_add_i32 s58, s62, s88
	v_lshl_add_u64 v[192:193], s[60:61], 0, v[178:179]
	s_mov_b32 m0, s58
	ds_read_b128 v[164:167], v208 offset:16384
	ds_read_b128 v[168:171], v208 offset:17408
	ds_read_b128 v[184:187], v208 offset:18432
	ds_read_b128 v[188:191], v208 offset:19456
	ds_read_b128 v[196:199], v208 offset:20480
	ds_read_b128 v[200:203], v208 offset:21504
	ds_read_b128 v[210:213], v208 offset:22528
	ds_read_b128 v[214:217], v208 offset:23552
	global_load_lds_dwordx4 v[192:193], off
	s_add_i32 m0, s58, 0x2000
	s_add_u32 s58, s60, s94
	v_lshl_add_u64 v[204:205], s[60:61], 0, v[174:175]
	s_addc_u32 s59, s61, 0
	s_add_i32 s60, s63, s88
	global_load_lds_dwordx4 v[204:205], off
	v_lshl_add_u64 v[218:219], s[58:59], 0, v[178:179]
	s_mov_b32 m0, s60
	v_lshl_add_u64 v[220:221], s[58:59], 0, v[174:175]
	global_load_lds_dwordx4 v[218:219], off
	s_add_i32 m0, s60, 0x2000
	v_lshl_add_u64 v[2:3], s[8:9], 0, v[176:177]
	global_load_lds_dwordx4 v[220:221], off
	s_mov_b32 m0, s89
	s_nop 0
	global_load_lds_dwordx4 v[2:3], off
	v_lshl_add_u64 v[2:3], s[8:9], 0, v[172:173]
	s_mov_b32 m0, s90
	s_nop 0
	global_load_lds_dwordx4 v[2:3], off
	s_waitcnt vmcnt(8)
	s_waitcnt lgkmcnt(0)
	s_barrier
	s_setprio 1
	s_waitcnt lgkmcnt(0)
	v_mfma_f32_16x16x32_bf16 v[60:63], v[132:135], v[164:167], v[60:63]
	v_mfma_f32_16x16x32_bf16 v[52:55], v[140:143], v[164:167], v[52:55]
	v_mfma_f32_16x16x32_bf16 v[44:47], v[132:135], v[184:187], v[44:47]
	v_mfma_f32_16x16x32_bf16 v[36:39], v[140:143], v[184:187], v[36:39]
	v_mfma_f32_16x16x32_bf16 v[28:31], v[132:135], v[196:199], v[28:31]
	v_mfma_f32_16x16x32_bf16 v[20:23], v[140:143], v[196:199], v[20:23]
	v_mfma_f32_16x16x32_bf16 v[12:15], v[132:135], v[210:213], v[12:15]
	v_mfma_f32_16x16x32_bf16 v[2:5], v[140:143], v[210:213], v[4:7]
	v_mfma_f32_16x16x32_bf16 v[60:63], v[136:139], v[168:171], v[60:63]
	v_mfma_f32_16x16x32_bf16 v[52:55], v[144:147], v[168:171], v[52:55]
	v_mfma_f32_16x16x32_bf16 v[44:47], v[136:139], v[188:191], v[44:47]
	v_mfma_f32_16x16x32_bf16 v[36:39], v[144:147], v[188:191], v[36:39]
	v_mfma_f32_16x16x32_bf16 v[28:31], v[136:139], v[200:203], v[28:31]
	v_mfma_f32_16x16x32_bf16 v[20:23], v[144:147], v[200:203], v[20:23]
	v_mfma_f32_16x16x32_bf16 v[12:15], v[136:139], v[214:217], v[12:15]
	v_mfma_f32_16x16x32_bf16 v[2:5], v[144:147], v[214:217], v[2:5]
	s_setprio 0
	s_setprio 1
	v_mfma_f32_16x16x32_bf16 v[64:67], v[148:151], v[164:167], v[64:67]
	v_mfma_f32_16x16x32_bf16 v[56:59], v[156:159], v[164:167], v[56:59]
	v_mfma_f32_16x16x32_bf16 v[48:51], v[148:151], v[184:187], v[48:51]
	v_mfma_f32_16x16x32_bf16 v[40:43], v[156:159], v[184:187], v[40:43]
	v_mfma_f32_16x16x32_bf16 v[32:35], v[148:151], v[196:199], v[32:35]
	v_mfma_f32_16x16x32_bf16 v[24:27], v[156:159], v[196:199], v[24:27]
	v_mfma_f32_16x16x32_bf16 v[16:19], v[148:151], v[210:213], v[16:19]
	v_mfma_f32_16x16x32_bf16 v[6:9], v[156:159], v[210:213], v[8:11]
	v_mfma_f32_16x16x32_bf16 v[64:67], v[152:155], v[168:171], v[64:67]
	v_mfma_f32_16x16x32_bf16 v[56:59], v[160:163], v[168:171], v[56:59]
	v_mfma_f32_16x16x32_bf16 v[48:51], v[152:155], v[188:191], v[48:51]
	v_mfma_f32_16x16x32_bf16 v[40:43], v[160:163], v[188:191], v[40:43]
	v_mfma_f32_16x16x32_bf16 v[32:35], v[152:155], v[200:203], v[32:35]
	v_mfma_f32_16x16x32_bf16 v[24:27], v[160:163], v[200:203], v[24:27]
	v_mfma_f32_16x16x32_bf16 v[16:19], v[152:155], v[214:217], v[16:19]
	v_mfma_f32_16x16x32_bf16 v[8:11], v[160:163], v[214:217], v[6:9]
	s_setprio 0
	s_barrier
; #define PG8_STAGE(bufoff, gbase, voff) do { _Pragma("unroll") for (int _i = 0; _i < 2; ++_i) \
;         __builtin_amdgcn_global_load_lds((const unsigned*)((const char*)(gbase) + (voff)[_i]), (PG8_LAS unsigned*)(lds + (bufoff) + ldsw + _i * 8192), 16, 0, 0); } while (0)
; #define PG8_LDA(dst, b, h) do { _Pragma("unroll") for (int m = 0; m < 4; ++m) _Pragma("unroll") for (int k = 0; k < 2; ++k) dst[m][k] = *(const PG8_LAS bf16x8*)(lds + PG8_SA(b, h) + aoff + m * 2048 + k * 1024); } while (0)
; #define PG8_LDB(dst, b, h) do { _Pragma("unroll") for (int n = 0; n < 2; ++n) _Pragma("unroll") for (int k = 0; k < 2; ++k) dst[n][k] = *(const PG8_LAS bf16x8*)(lds + PG8_SB(b, h) + boff + n * 2048 + k * 1024); } while (0)
; #define PG8_MMA(ai, bj, At, Bt) do { __builtin_amdgcn_s_setprio(1); _Pragma("unroll") for (int m = 0; m < 4; ++m) _Pragma("unroll") for (int n = 0; n < 2; ++n) _Pragma("unroll") for (int k = 0; k < 2; ++k) \
;         acc[ai][bj][m][n] = __builtin_amdgcn_mfma_f32_16x16x32_bf16(Bt[n][k], At[m][k], acc[ai][bj][m][n], 0, 0, 0); __builtin_amdgcn_s_setprio(0); } while (0)
; #define PG8_WAIT_V(n) asm volatile("s_waitcnt vmcnt(" #n ")" ::: "memory")
; #define PG8_WAIT_L(n) asm volatile("s_waitcnt lgkmcnt(" #n ")" ::: "memory")
; #define PG8_BAR __builtin_amdgcn_s_barrier()
; #define PG8_SCHED __builtin_amdgcn_sched_barrier(0)
; template <class Epi, class Sched, bool ALIGN_EPI = false, bool SP2 = false>
; __device__ __forceinline__ void gemm_phase(PG8_LAS unsigned char* lds, const Gemm g, const Sched& S, const Epi& E, int tid_in) {
;     ...
;             PG8_LDB(B0, 1, 0); PG8_LDB(B1, 1, 1); PG8_SCHED; PG8_LDA(At, 1, 0); PG8_STAGE(PG8_SA(0, 1), a2 + hstepA, voffA);
;             PG8_WAIT_V(8); PG8_WAIT_L(0); PG8_BAR; PG8_MMA(0, 0, At, B0); PG8_MMA(0, 1, At, B1); PG8_BAR; PG8_SCHED;
;             PG8_LDA(At, 1, 1); PG8_STAGE(PG8_SB(1, 0), b3, voffB); PG8_STAGE(PG8_SB(1, 1), b3 + hstep, voffB); PG8_STAGE(PG8_SA(1, 0), a3, voffA);
;             PG8_WAIT_V(8); PG8_WAIT_L(0); PG8_BAR; PG8_MMA(1, 0, At, B0); PG8_MMA(1, 1, At, B1); PG8_BAR; PG8_SCHED;
	s_add_i32 s58, 0, 0x18000
	v_add_u32_e32 v0, s58, v207
	s_add_i32 s59, 0, 0x1c000
	ds_read_b128 v[132:135], v0
	ds_read_b128 v[136:139], v0 offset:1024
	ds_read_b128 v[140:143], v0 offset:2048
	ds_read_b128 v[144:147], v0 offset:3072
	v_add_u32_e32 v0, s59, v207
	ds_read_b128 v[148:151], v0
	ds_read_b128 v[152:155], v0 offset:1024
	ds_read_b128 v[156:159], v0 offset:2048
	ds_read_b128 v[160:163], v0 offset:3072
	s_add_u32 s8, s8, s94
	s_addc_u32 s9, s9, 0
	s_mov_b32 m0, s91
	v_lshl_add_u64 v[6:7], s[8:9], 0, v[176:177]
	ds_read_b128 v[164:167], v208 offset:32768
	ds_read_b128 v[168:171], v208 offset:33792
	ds_read_b128 v[184:187], v208 offset:34816
	ds_read_b128 v[188:191], v208 offset:35840
	ds_read_b128 v[196:199], v208 offset:36864
	ds_read_b128 v[200:203], v208 offset:37888
	ds_read_b128 v[210:213], v208 offset:38912
	ds_read_b128 v[214:217], v208 offset:39936
	global_load_lds_dwordx4 v[6:7], off
	v_lshl_add_u64 v[6:7], s[8:9], 0, v[172:173]
	s_mov_b32 m0, s92
	s_nop 0
	global_load_lds_dwordx4 v[6:7], off
	s_waitcnt vmcnt(8)
	s_waitcnt lgkmcnt(0)
	s_barrier
	s_setprio 1
	s_waitcnt lgkmcnt(0)
	v_mfma_f32_16x16x32_bf16 v[124:127], v[132:135], v[164:167], v[124:127]
	v_mfma_f32_16x16x32_bf16 v[116:119], v[140:143], v[164:167], v[116:119]
	v_mfma_f32_16x16x32_bf16 v[108:111], v[132:135], v[184:187], v[108:111]
	v_mfma_f32_16x16x32_bf16 v[100:103], v[140:143], v[184:187], v[100:103]
	v_mfma_f32_16x16x32_bf16 v[92:95], v[132:135], v[196:199], v[92:95]
	v_mfma_f32_16x16x32_bf16 v[84:87], v[140:143], v[196:199], v[84:87]
	v_mfma_f32_16x16x32_bf16 v[76:79], v[132:135], v[210:213], v[76:79]
	v_mfma_f32_16x16x32_bf16 v[68:71], v[140:143], v[210:213], v[68:71]
	v_mfma_f32_16x16x32_bf16 v[124:127], v[136:139], v[168:171], v[124:127]
	v_mfma_f32_16x16x32_bf16 v[116:119], v[144:147], v[168:171], v[116:119]
	v_mfma_f32_16x16x32_bf16 v[108:111], v[136:139], v[188:191], v[108:111]
	v_mfma_f32_16x16x32_bf16 v[100:103], v[144:147], v[188:191], v[100:103]
	v_mfma_f32_16x16x32_bf16 v[92:95], v[136:139], v[200:203], v[92:95]
	v_mfma_f32_16x16x32_bf16 v[84:87], v[144:147], v[200:203], v[84:87]
	v_mfma_f32_16x16x32_bf16 v[76:79], v[136:139], v[214:217], v[76:79]
	v_mfma_f32_16x16x32_bf16 v[68:71], v[144:147], v[214:217], v[68:71]
	s_setprio 0
	s_setprio 1
	v_mfma_f32_16x16x32_bf16 v[128:131], v[148:151], v[164:167], v[128:131]
	v_mfma_f32_16x16x32_bf16 v[120:123], v[156:159], v[164:167], v[120:123]
	v_mfma_f32_16x16x32_bf16 v[112:115], v[148:151], v[184:187], v[112:115]
	v_mfma_f32_16x16x32_bf16 v[104:107], v[156:159], v[184:187], v[104:107]
	v_mfma_f32_16x16x32_bf16 v[96:99], v[148:151], v[196:199], v[96:99]
	v_mfma_f32_16x16x32_bf16 v[88:91], v[156:159], v[196:199], v[88:91]
	v_mfma_f32_16x16x32_bf16 v[80:83], v[148:151], v[210:213], v[80:83]
	v_mfma_f32_16x16x32_bf16 v[72:75], v[156:159], v[210:213], v[72:75]
	v_mfma_f32_16x16x32_bf16 v[128:131], v[152:155], v[168:171], v[128:131]
	v_mfma_f32_16x16x32_bf16 v[120:123], v[160:163], v[168:171], v[120:123]
	v_mfma_f32_16x16x32_bf16 v[112:115], v[152:155], v[188:191], v[112:115]
	v_mfma_f32_16x16x32_bf16 v[104:107], v[160:163], v[188:191], v[104:107]
	v_mfma_f32_16x16x32_bf16 v[96:99], v[152:155], v[200:203], v[96:99]
	v_mfma_f32_16x16x32_bf16 v[88:91], v[160:163], v[200:203], v[88:91]
	v_mfma_f32_16x16x32_bf16 v[80:83], v[152:155], v[214:217], v[80:83]
	v_mfma_f32_16x16x32_bf16 v[72:75], v[160:163], v[214:217], v[72:75]
	s_setprio 0
	s_barrier
	s_add_i32 s8, s58, s88
	v_lshl_add_u64 v[6:7], v[192:193], 0, s[96:97]
	s_mov_b32 m0, s8
	ds_read_b128 v[164:167], v208 offset:49152
	ds_read_b128 v[168:171], v208 offset:50176
	ds_read_b128 v[184:187], v208 offset:51200
	ds_read_b128 v[188:191], v208 offset:52224
	ds_read_b128 v[196:199], v208 offset:53248
	ds_read_b128 v[200:203], v208 offset:54272
	ds_read_b128 v[210:213], v208 offset:55296
	ds_read_b128 v[214:217], v208 offset:56320
	global_load_lds_dwordx4 v[6:7], off
	v_lshl_add_u64 v[6:7], v[204:205], 0, s[96:97]
	s_add_i32 m0, s8, 0x2000
	s_add_i32 s8, s59, s88
	global_load_lds_dwordx4 v[6:7], off
	v_lshl_add_u64 v[6:7], v[218:219], 0, s[96:97]
	s_mov_b32 m0, s8
	s_nop 0
	global_load_lds_dwordx4 v[6:7], off
	v_lshl_add_u64 v[6:7], v[220:221], 0, s[96:97]
	s_add_i32 m0, s8, 0x2000
	s_nop 0
	global_load_lds_dwordx4 v[6:7], off
	v_lshl_add_u64 v[6:7], s[0:1], 0, v[176:177]
	s_mov_b32 m0, s93
	s_nop 0
	global_load_lds_dwordx4 v[6:7], off
	v_lshl_add_u64 v[6:7], s[0:1], 0, v[172:173]
	s_mov_b32 m0, s78
	s_nop 0
	global_load_lds_dwordx4 v[6:7], off
	s_waitcnt vmcnt(8)
	s_waitcnt lgkmcnt(0)
	s_barrier
	s_setprio 1
	s_waitcnt lgkmcnt(0)
	v_mfma_f32_16x16x32_bf16 v[60:63], v[132:135], v[164:167], v[60:63]
	v_mfma_f32_16x16x32_bf16 v[52:55], v[140:143], v[164:167], v[52:55]
	v_mfma_f32_16x16x32_bf16 v[44:47], v[132:135], v[184:187], v[44:47]
	v_mfma_f32_16x16x32_bf16 v[36:39], v[140:143], v[184:187], v[36:39]
	v_mfma_f32_16x16x32_bf16 v[28:31], v[132:135], v[196:199], v[28:31]
	v_mfma_f32_16x16x32_bf16 v[20:23], v[140:143], v[196:199], v[20:23]
	v_mfma_f32_16x16x32_bf16 v[12:15], v[132:135], v[210:213], v[12:15]
	v_mfma_f32_16x16x32_bf16 v[2:5], v[140:143], v[210:213], v[2:5]
	v_mfma_f32_16x16x32_bf16 v[60:63], v[136:139], v[168:171], v[60:63]
	v_mfma_f32_16x16x32_bf16 v[52:55], v[144:147], v[168:171], v[52:55]
	v_mfma_f32_16x16x32_bf16 v[44:47], v[136:139], v[188:191], v[44:47]
	v_mfma_f32_16x16x32_bf16 v[36:39], v[144:147], v[188:191], v[36:39]
	v_mfma_f32_16x16x32_bf16 v[28:31], v[136:139], v[200:203], v[28:31]
	v_mfma_f32_16x16x32_bf16 v[20:23], v[144:147], v[200:203], v[20:23]
	v_mfma_f32_16x16x32_bf16 v[12:15], v[136:139], v[214:217], v[12:15]
	v_mfma_f32_16x16x32_bf16 v[4:7], v[144:147], v[214:217], v[2:5]
	s_setprio 0
	s_setprio 1
	v_mfma_f32_16x16x32_bf16 v[64:67], v[148:151], v[164:167], v[64:67]
	v_mfma_f32_16x16x32_bf16 v[56:59], v[156:159], v[164:167], v[56:59]
	v_mfma_f32_16x16x32_bf16 v[48:51], v[148:151], v[184:187], v[48:51]
	v_mfma_f32_16x16x32_bf16 v[40:43], v[156:159], v[184:187], v[40:43]
	v_mfma_f32_16x16x32_bf16 v[32:35], v[148:151], v[196:199], v[32:35]
	v_mfma_f32_16x16x32_bf16 v[24:27], v[156:159], v[196:199], v[24:27]
	v_mfma_f32_16x16x32_bf16 v[16:19], v[148:151], v[210:213], v[16:19]
	v_mfma_f32_16x16x32_bf16 v[8:11], v[156:159], v[210:213], v[8:11]
	v_mfma_f32_16x16x32_bf16 v[64:67], v[152:155], v[168:171], v[64:67]
	v_mfma_f32_16x16x32_bf16 v[56:59], v[160:163], v[168:171], v[56:59]
	v_mfma_f32_16x16x32_bf16 v[48:51], v[152:155], v[188:191], v[48:51]
	v_mfma_f32_16x16x32_bf16 v[40:43], v[160:163], v[188:191], v[40:43]
	v_mfma_f32_16x16x32_bf16 v[32:35], v[152:155], v[200:203], v[32:35]
	v_mfma_f32_16x16x32_bf16 v[24:27], v[160:163], v[200:203], v[24:27]
	v_mfma_f32_16x16x32_bf16 v[16:19], v[152:155], v[214:217], v[16:19]
	v_mfma_f32_16x16x32_bf16 v[8:11], v[160:163], v[214:217], v[8:11]
	s_setprio 0
	s_barrier
	s_add_u32 s6, s6, 0x100
	s_addc_u32 s7, s7, 0
	s_add_u32 s54, s54, 0x100
	s_addc_u32 s55, s55, 0
	s_add_i32 s56, s56, -2
	s_cmp_ge_u32 s57, s18
	s_mov_b32 s0, s57
	s_cbranch_scc0 .LBB0_1180
	s_branch .Lyk1_exit
; #define PG8_STAGE(bufoff, gbase, voff) do { _Pragma("unroll") for (int _i = 0; _i < 2; ++_i) \
;         __builtin_amdgcn_global_load_lds((const unsigned*)((const char*)(gbase) + (voff)[_i]), (PG8_LAS unsigned*)(lds + (bufoff) + ldsw + _i * 8192), 16, 0, 0); } while (0)
; #define PG8_LDA(dst, b, h) do { _Pragma("unroll") for (int m = 0; m < 4; ++m) _Pragma("unroll") for (int k = 0; k < 2; ++k) dst[m][k] = *(const PG8_LAS bf16x8*)(lds + PG8_SA(b, h) + aoff + m * 2048 + k * 1024); } while (0)
; #define PG8_LDB(dst, b, h) do { _Pragma("unroll") for (int n = 0; n < 2; ++n) _Pragma("unroll") for (int k = 0; k < 2; ++k) dst[n][k] = *(const PG8_LAS bf16x8*)(lds + PG8_SB(b, h) + boff + n * 2048 + k * 1024); } while (0)
; #define PG8_MMA(ai, bj, At, Bt) do { __builtin_amdgcn_s_setprio(1); _Pragma("unroll") for (int m = 0; m < 4; ++m) _Pragma("unroll") for (int n = 0; n < 2; ++n) _Pragma("unroll") for (int k = 0; k < 2; ++k) \
;         acc[ai][bj][m][n] = __builtin_amdgcn_mfma_f32_16x16x32_bf16(Bt[n][k], At[m][k], acc[ai][bj][m][n], 0, 0, 0); __builtin_amdgcn_s_setprio(0); } while (0)
; #define PG8_WAIT_V(n) asm volatile("s_waitcnt vmcnt(" #n ")" ::: "memory")
; #define PG8_WAIT_L(n) asm volatile("s_waitcnt lgkmcnt(" #n ")" ::: "memory")
; #define PG8_BAR __builtin_amdgcn_s_barrier()
; #define PG8_SCHED __builtin_amdgcn_sched_barrier(0)
; template <class Epi, class Sched, bool ALIGN_EPI = false, bool SP2 = false>
; __device__ __forceinline__ void gemm_phase(PG8_LAS unsigned char* lds, const Gemm g, const Sched& S, const Epi& E, int tid_in) {
;     ...
;             const bool last = (t == ntc - 2);
;             const char* a1 = PG8_KA(cA, t + 1);
;             const char* a2 = last ? nA : PG8_KA(cA, t + 2); const char* b2 = last ? nB : cB + (size_t)(t + 2) * kstep;
;             const char* a3 = last ? PG8_KA(nA, 1) : PG8_KA(cA, t + 3); const char* b3 = b2 + kstep;
;             if (last && has_next) S.a_ready(nxt);
;             if constexpr (SP2) {
;             PG8_LDB(B0, 0, 0); PG8_LDB(B1, 0, 1); PG8_SCHED; PG8_LDA(At, 0, 0); PG8_STAGE(PG8_SA(1, 1), a1 + hstepA, voffA);
;             PG8_WAIT_V(8); PG8_WAIT_L(0); PG8_BAR; PG8_MMA(0, 0, At, B0); PG8_MMA(0, 1, At, B1); PG8_BAR; PG8_SCHED;
;             PG8_LDA(At, 0, 1); PG8_STAGE(PG8_SB(0, 0), b2, voffB); PG8_STAGE(PG8_SB(0, 1), b2 + hstep, voffB); PG8_STAGE(PG8_SA(0, 0), a2, voffA);
.Lyk1_loop:
	s_or_b32 s1, s0, 1
	s_cmp_ge_u32 s1, s84
	s_cselect_b32 s58, s86, 0
	s_cselect_b32 s59, s85, 0
	s_add_i32 s57, s0, 2
	s_cmp_ge_u32 s57, s84
	s_cselect_b32 s8, s86, 0
	s_cselect_b32 s1, s85, 0
	s_add_u32 s8, s6, s8
	s_addc_u32 s1, s7, s1
	s_add_u32 s8, s8, 0x100
	s_addc_u32 s1, s1, 0
	s_add_i32 s0, s0, 3
	s_cmp_ge_u32 s0, s84
	s_cselect_b32 s9, s86, 0
	s_cselect_b32 s0, s85, 0
	s_add_u32 s9, s6, s9
	s_addc_u32 s0, s7, s0
	s_add_u32 s62, s9, 0x180
	s_addc_u32 s0, s0, 0
	s_cmp_eq_u32 s56, 0
	s_cselect_b32 s9, s49, s1
	s_cselect_b32 s8, s48, s8
	s_cselect_b32 s61, s51, s55
	s_cselect_b32 s60, s50, s54
	s_cselect_b32 s1, s53, s0
	s_cselect_b32 s0, s21, s62
	s_add_i32 s62, 0, 0x10000
	v_add_u32_e32 v0, s62, v207
	s_add_i32 s63, 0, 0x14000
	ds_read_b128 v[132:135], v0
	ds_read_b128 v[136:139], v0 offset:1024
	ds_read_b128 v[140:143], v0 offset:2048
	ds_read_b128 v[144:147], v0 offset:3072
	v_add_u32_e32 v0, s63, v207
	ds_read_b128 v[148:151], v0
	ds_read_b128 v[152:155], v0 offset:1024
	ds_read_b128 v[156:159], v0 offset:2048
	ds_read_b128 v[160:163], v0 offset:3072
	v_lshl_add_u64 v[2:3], s[6:7], 0, v[180:181]
	v_lshl_add_u64 v[2:3], v[2:3], 0, s[58:59]
	s_add_i32 m0, s89, 0xc000
	ds_read_b128 v[164:167], v208
	ds_read_b128 v[168:171], v208 offset:1024
	ds_read_b128 v[184:187], v208 offset:2048
	ds_read_b128 v[188:191], v208 offset:3072
	ds_read_b128 v[196:199], v208 offset:4096
	ds_read_b128 v[200:203], v208 offset:5120
	ds_read_b128 v[210:213], v208 offset:6144
	ds_read_b128 v[214:217], v208 offset:7168
	global_load_lds_dwordx4 v[2:3], off
	v_lshl_add_u64 v[2:3], s[6:7], 0, v[182:183]
	v_lshl_add_u64 v[2:3], v[2:3], 0, s[58:59]
	s_add_i32 m0, s89, 0xe000
	s_nop 0
	global_load_lds_dwordx4 v[2:3], off
	s_waitcnt vmcnt(8)
	s_waitcnt lgkmcnt(0)
	s_barrier
	s_setprio 2
	s_waitcnt lgkmcnt(0)
	v_mfma_f32_16x16x32_bf16 v[124:127], v[132:135], v[164:167], v[124:127]
	v_mfma_f32_16x16x32_bf16 v[116:119], v[140:143], v[164:167], v[116:119]
	v_mfma_f32_16x16x32_bf16 v[108:111], v[132:135], v[184:187], v[108:111]
	v_mfma_f32_16x16x32_bf16 v[100:103], v[140:143], v[184:187], v[100:103]
	v_mfma_f32_16x16x32_bf16 v[92:95], v[132:135], v[196:199], v[92:95]
	v_mfma_f32_16x16x32_bf16 v[84:87], v[140:143], v[196:199], v[84:87]
	v_mfma_f32_16x16x32_bf16 v[76:79], v[132:135], v[210:213], v[76:79]
	v_mfma_f32_16x16x32_bf16 v[68:71], v[140:143], v[210:213], v[68:71]
	v_mfma_f32_16x16x32_bf16 v[124:127], v[136:139], v[168:171], v[124:127]
	v_mfma_f32_16x16x32_bf16 v[116:119], v[144:147], v[168:171], v[116:119]
	v_mfma_f32_16x16x32_bf16 v[108:111], v[136:139], v[188:191], v[108:111]
	v_mfma_f32_16x16x32_bf16 v[100:103], v[144:147], v[188:191], v[100:103]
	v_mfma_f32_16x16x32_bf16 v[92:95], v[136:139], v[200:203], v[92:95]
	v_mfma_f32_16x16x32_bf16 v[84:87], v[144:147], v[200:203], v[84:87]
	v_mfma_f32_16x16x32_bf16 v[76:79], v[136:139], v[214:217], v[76:79]
	v_mfma_f32_16x16x32_bf16 v[68:71], v[144:147], v[214:217], v[68:71]
	s_setprio 1
	s_setprio 2
	v_mfma_f32_16x16x32_bf16 v[128:131], v[148:151], v[164:167], v[128:131]
	v_mfma_f32_16x16x32_bf16 v[120:123], v[156:159], v[164:167], v[120:123]
	v_mfma_f32_16x16x32_bf16 v[112:115], v[148:151], v[184:187], v[112:115]
	v_mfma_f32_16x16x32_bf16 v[104:107], v[156:159], v[184:187], v[104:107]
	v_mfma_f32_16x16x32_bf16 v[96:99], v[148:151], v[196:199], v[96:99]
	v_mfma_f32_16x16x32_bf16 v[88:91], v[156:159], v[196:199], v[88:91]
	v_mfma_f32_16x16x32_bf16 v[80:83], v[148:151], v[210:213], v[80:83]
	v_mfma_f32_16x16x32_bf16 v[72:75], v[156:159], v[210:213], v[72:75]
	v_mfma_f32_16x16x32_bf16 v[128:131], v[152:155], v[168:171], v[128:131]
	v_mfma_f32_16x16x32_bf16 v[120:123], v[160:163], v[168:171], v[120:123]
	v_mfma_f32_16x16x32_bf16 v[112:115], v[152:155], v[188:191], v[112:115]
	v_mfma_f32_16x16x32_bf16 v[104:107], v[160:163], v[188:191], v[104:107]
	v_mfma_f32_16x16x32_bf16 v[96:99], v[152:155], v[200:203], v[96:99]
	v_mfma_f32_16x16x32_bf16 v[88:91], v[160:163], v[200:203], v[88:91]
	v_mfma_f32_16x16x32_bf16 v[80:83], v[152:155], v[214:217], v[80:83]
	v_mfma_f32_16x16x32_bf16 v[72:75], v[160:163], v[214:217], v[72:75]
	s_setprio 1
	s_barrier
	s_add_i32 s58, s62, s88
	v_lshl_add_u64 v[192:193], s[60:61], 0, v[178:179]
	s_mov_b32 m0, s58
	ds_read_b128 v[164:167], v208 offset:16384
	ds_read_b128 v[168:171], v208 offset:17408
	ds_read_b128 v[184:187], v208 offset:18432
	ds_read_b128 v[188:191], v208 offset:19456
	ds_read_b128 v[196:199], v208 offset:20480
	ds_read_b128 v[200:203], v208 offset:21504
	ds_read_b128 v[210:213], v208 offset:22528
	ds_read_b128 v[214:217], v208 offset:23552
	global_load_lds_dwordx4 v[192:193], off
	s_add_i32 m0, s58, 0x2000
	s_add_u32 s58, s60, s94
	v_lshl_add_u64 v[204:205], s[60:61], 0, v[174:175]
	s_addc_u32 s59, s61, 0
	s_add_i32 s60, s63, s88
	global_load_lds_dwordx4 v[204:205], off
	v_lshl_add_u64 v[218:219], s[58:59], 0, v[178:179]
	s_mov_b32 m0, s60
	v_lshl_add_u64 v[220:221], s[58:59], 0, v[174:175]
	global_load_lds_dwordx4 v[218:219], off
	s_add_i32 m0, s60, 0x2000
	v_lshl_add_u64 v[2:3], s[8:9], 0, v[176:177]
	global_load_lds_dwordx4 v[220:221], off
	s_mov_b32 m0, s89
	s_nop 0
	global_load_lds_dwordx4 v[2:3], off
	v_lshl_add_u64 v[2:3], s[8:9], 0, v[172:173]
	s_mov_b32 m0, s90
	s_nop 0
	global_load_lds_dwordx4 v[2:3], off
	s_waitcnt vmcnt(8)
	s_waitcnt lgkmcnt(0)
	s_barrier
; #define PG8_STAGE(bufoff, gbase, voff) do { _Pragma("unroll") for (int _i = 0; _i < 2; ++_i) \
;         __builtin_amdgcn_global_load_lds((const unsigned*)((const char*)(gbase) + (voff)[_i]), (PG8_LAS unsigned*)(lds + (bufoff) + ldsw + _i * 8192), 16, 0, 0); } while (0)
; #define PG8_LDA(dst, b, h) do { _Pragma("unroll") for (int m = 0; m < 4; ++m) _Pragma("unroll") for (int k = 0; k < 2; ++k) dst[m][k] = *(const PG8_LAS bf16x8*)(lds + PG8_SA(b, h) + aoff + m * 2048 + k * 1024); } while (0)
; #define PG8_LDB(dst, b, h) do { _Pragma("unroll") for (int n = 0; n < 2; ++n) _Pragma("unroll") for (int k = 0; k < 2; ++k) dst[n][k] = *(const PG8_LAS bf16x8*)(lds + PG8_SB(b, h) + boff + n * 2048 + k * 1024); } while (0)
; #define PG8_MMA(ai, bj, At, Bt) do { __builtin_amdgcn_s_setprio(1); _Pragma("unroll") for (int m = 0; m < 4; ++m) _Pragma("unroll") for (int n = 0; n < 2; ++n) _Pragma("unroll") for (int k = 0; k < 2; ++k) \
;         acc[ai][bj][m][n] = __builtin_amdgcn_mfma_f32_16x16x32_bf16(Bt[n][k], At[m][k], acc[ai][bj][m][n], 0, 0, 0); __builtin_amdgcn_s_setprio(0); } while (0)
; #define PG8_WAIT_V(n) asm volatile("s_waitcnt vmcnt(" #n ")" ::: "memory")
; #define PG8_WAIT_L(n) asm volatile("s_waitcnt lgkmcnt(" #n ")" ::: "memory")
; #define PG8_BAR __builtin_amdgcn_s_barrier()
; #define PG8_SCHED __builtin_amdgcn_sched_barrier(0)
; template <class Epi, class Sched, bool ALIGN_EPI = false, bool SP2 = false>
; __device__ __forceinline__ void gemm_phase(PG8_LAS unsigned char* lds, const Gemm g, const Sched& S, const Epi& E, int tid_in) {
;     ...
;             PG8_WAIT_V(8); PG8_WAIT_L(0); PG8_BAR; PG8_MMA(1, 0, At, B0); PG8_MMA(1, 1, At, B1); PG8_BAR; PG8_SCHED;
;             PG8_LDB(B0, 1, 0); PG8_LDB(B1, 1, 1); PG8_SCHED; PG8_LDA(At, 1, 0); PG8_STAGE(PG8_SA(0, 1), a2 + hstepA, voffA);
;             PG8_WAIT_V(8); PG8_WAIT_L(0); PG8_BAR; PG8_MMA(0, 0, At, B0); PG8_MMA(0, 1, At, B1); PG8_BAR; PG8_SCHED;
;             PG8_LDA(At, 1, 1); PG8_STAGE(PG8_SB(1, 0), b3, voffB); PG8_STAGE(PG8_SB(1, 1), b3 + hstep, voffB); PG8_STAGE(PG8_SA(1, 0), a3, voffA);
	s_setprio 2
	s_waitcnt lgkmcnt(0)
	v_mfma_f32_16x16x32_bf16 v[60:63], v[132:135], v[164:167], v[60:63]
	v_mfma_f32_16x16x32_bf16 v[52:55], v[140:143], v[164:167], v[52:55]
	v_mfma_f32_16x16x32_bf16 v[44:47], v[132:135], v[184:187], v[44:47]
	v_mfma_f32_16x16x32_bf16 v[36:39], v[140:143], v[184:187], v[36:39]
	v_mfma_f32_16x16x32_bf16 v[28:31], v[132:135], v[196:199], v[28:31]
	v_mfma_f32_16x16x32_bf16 v[20:23], v[140:143], v[196:199], v[20:23]
	v_mfma_f32_16x16x32_bf16 v[12:15], v[132:135], v[210:213], v[12:15]
	v_mfma_f32_16x16x32_bf16 v[2:5], v[140:143], v[210:213], v[4:7]
	v_mfma_f32_16x16x32_bf16 v[60:63], v[136:139], v[168:171], v[60:63]
	v_mfma_f32_16x16x32_bf16 v[52:55], v[144:147], v[168:171], v[52:55]
	v_mfma_f32_16x16x32_bf16 v[44:47], v[136:139], v[188:191], v[44:47]
	v_mfma_f32_16x16x32_bf16 v[36:39], v[144:147], v[188:191], v[36:39]
	v_mfma_f32_16x16x32_bf16 v[28:31], v[136:139], v[200:203], v[28:31]
	v_mfma_f32_16x16x32_bf16 v[20:23], v[144:147], v[200:203], v[20:23]
	v_mfma_f32_16x16x32_bf16 v[12:15], v[136:139], v[214:217], v[12:15]
	v_mfma_f32_16x16x32_bf16 v[2:5], v[144:147], v[214:217], v[2:5]
	s_setprio 1
	s_setprio 2
	v_mfma_f32_16x16x32_bf16 v[64:67], v[148:151], v[164:167], v[64:67]
	v_mfma_f32_16x16x32_bf16 v[56:59], v[156:159], v[164:167], v[56:59]
	v_mfma_f32_16x16x32_bf16 v[48:51], v[148:151], v[184:187], v[48:51]
	v_mfma_f32_16x16x32_bf16 v[40:43], v[156:159], v[184:187], v[40:43]
	v_mfma_f32_16x16x32_bf16 v[32:35], v[148:151], v[196:199], v[32:35]
	v_mfma_f32_16x16x32_bf16 v[24:27], v[156:159], v[196:199], v[24:27]
	v_mfma_f32_16x16x32_bf16 v[16:19], v[148:151], v[210:213], v[16:19]
	v_mfma_f32_16x16x32_bf16 v[6:9], v[156:159], v[210:213], v[8:11]
	v_mfma_f32_16x16x32_bf16 v[64:67], v[152:155], v[168:171], v[64:67]
	v_mfma_f32_16x16x32_bf16 v[56:59], v[160:163], v[168:171], v[56:59]
	v_mfma_f32_16x16x32_bf16 v[48:51], v[152:155], v[188:191], v[48:51]
	v_mfma_f32_16x16x32_bf16 v[40:43], v[160:163], v[188:191], v[40:43]
	v_mfma_f32_16x16x32_bf16 v[32:35], v[152:155], v[200:203], v[32:35]
	v_mfma_f32_16x16x32_bf16 v[24:27], v[160:163], v[200:203], v[24:27]
	v_mfma_f32_16x16x32_bf16 v[16:19], v[152:155], v[214:217], v[16:19]
	v_mfma_f32_16x16x32_bf16 v[8:11], v[160:163], v[214:217], v[6:9]
	s_setprio 1
	s_barrier
	s_add_i32 s58, 0, 0x18000
	v_add_u32_e32 v0, s58, v207
	s_add_i32 s59, 0, 0x1c000
	ds_read_b128 v[132:135], v0
	ds_read_b128 v[136:139], v0 offset:1024
	ds_read_b128 v[140:143], v0 offset:2048
	ds_read_b128 v[144:147], v0 offset:3072
	v_add_u32_e32 v0, s59, v207
	ds_read_b128 v[148:151], v0
	ds_read_b128 v[152:155], v0 offset:1024
	ds_read_b128 v[156:159], v0 offset:2048
	ds_read_b128 v[160:163], v0 offset:3072
	s_add_u32 s8, s8, s94
	s_addc_u32 s9, s9, 0
	s_mov_b32 m0, s91
	v_lshl_add_u64 v[6:7], s[8:9], 0, v[176:177]
	ds_read_b128 v[164:167], v208 offset:32768
	ds_read_b128 v[168:171], v208 offset:33792
	ds_read_b128 v[184:187], v208 offset:34816
	ds_read_b128 v[188:191], v208 offset:35840
	ds_read_b128 v[196:199], v208 offset:36864
	ds_read_b128 v[200:203], v208 offset:37888
	ds_read_b128 v[210:213], v208 offset:38912
	ds_read_b128 v[214:217], v208 offset:39936
	global_load_lds_dwordx4 v[6:7], off
	v_lshl_add_u64 v[6:7], s[8:9], 0, v[172:173]
	s_mov_b32 m0, s92
	s_nop 0
	global_load_lds_dwordx4 v[6:7], off
	s_waitcnt vmcnt(8)
	s_waitcnt lgkmcnt(0)
	s_barrier
	s_setprio 2
	s_waitcnt lgkmcnt(0)
	v_mfma_f32_16x16x32_bf16 v[124:127], v[132:135], v[164:167], v[124:127]
	v_mfma_f32_16x16x32_bf16 v[116:119], v[140:143], v[164:167], v[116:119]
	v_mfma_f32_16x16x32_bf16 v[108:111], v[132:135], v[184:187], v[108:111]
	v_mfma_f32_16x16x32_bf16 v[100:103], v[140:143], v[184:187], v[100:103]
	v_mfma_f32_16x16x32_bf16 v[92:95], v[132:135], v[196:199], v[92:95]
	v_mfma_f32_16x16x32_bf16 v[84:87], v[140:143], v[196:199], v[84:87]
	v_mfma_f32_16x16x32_bf16 v[76:79], v[132:135], v[210:213], v[76:79]
	v_mfma_f32_16x16x32_bf16 v[68:71], v[140:143], v[210:213], v[68:71]
	v_mfma_f32_16x16x32_bf16 v[124:127], v[136:139], v[168:171], v[124:127]
	v_mfma_f32_16x16x32_bf16 v[116:119], v[144:147], v[168:171], v[116:119]
	v_mfma_f32_16x16x32_bf16 v[108:111], v[136:139], v[188:191], v[108:111]
	v_mfma_f32_16x16x32_bf16 v[100:103], v[144:147], v[188:191], v[100:103]
	v_mfma_f32_16x16x32_bf16 v[92:95], v[136:139], v[200:203], v[92:95]
	v_mfma_f32_16x16x32_bf16 v[84:87], v[144:147], v[200:203], v[84:87]
	v_mfma_f32_16x16x32_bf16 v[76:79], v[136:139], v[214:217], v[76:79]
	v_mfma_f32_16x16x32_bf16 v[68:71], v[144:147], v[214:217], v[68:71]
	s_setprio 1
	s_setprio 2
	v_mfma_f32_16x16x32_bf16 v[128:131], v[148:151], v[164:167], v[128:131]
	v_mfma_f32_16x16x32_bf16 v[120:123], v[156:159], v[164:167], v[120:123]
	v_mfma_f32_16x16x32_bf16 v[112:115], v[148:151], v[184:187], v[112:115]
	v_mfma_f32_16x16x32_bf16 v[104:107], v[156:159], v[184:187], v[104:107]
	v_mfma_f32_16x16x32_bf16 v[96:99], v[148:151], v[196:199], v[96:99]
	v_mfma_f32_16x16x32_bf16 v[88:91], v[156:159], v[196:199], v[88:91]
	v_mfma_f32_16x16x32_bf16 v[80:83], v[148:151], v[210:213], v[80:83]
	v_mfma_f32_16x16x32_bf16 v[72:75], v[156:159], v[210:213], v[72:75]
	v_mfma_f32_16x16x32_bf16 v[128:131], v[152:155], v[168:171], v[128:131]
	v_mfma_f32_16x16x32_bf16 v[120:123], v[160:163], v[168:171], v[120:123]
	v_mfma_f32_16x16x32_bf16 v[112:115], v[152:155], v[188:191], v[112:115]
	v_mfma_f32_16x16x32_bf16 v[104:107], v[160:163], v[188:191], v[104:107]
	v_mfma_f32_16x16x32_bf16 v[96:99], v[152:155], v[200:203], v[96:99]
	v_mfma_f32_16x16x32_bf16 v[88:91], v[160:163], v[200:203], v[88:91]
	v_mfma_f32_16x16x32_bf16 v[80:83], v[152:155], v[214:217], v[80:83]
	v_mfma_f32_16x16x32_bf16 v[72:75], v[160:163], v[214:217], v[72:75]
	s_setprio 1
	s_barrier
; #define PG8_STAGE(bufoff, gbase, voff) do { _Pragma("unroll") for (int _i = 0; _i < 2; ++_i) \
;         __builtin_amdgcn_global_load_lds((const unsigned*)((const char*)(gbase) + (voff)[_i]), (PG8_LAS unsigned*)(lds + (bufoff) + ldsw + _i * 8192), 16, 0, 0); } while (0)
; #define PG8_LDA(dst, b, h) do { _Pragma("unroll") for (int m = 0; m < 4; ++m) _Pragma("unroll") for (int k = 0; k < 2; ++k) dst[m][k] = *(const PG8_LAS bf16x8*)(lds + PG8_SA(b, h) + aoff + m * 2048 + k * 1024); } while (0)
; #define PG8_MMA(ai, bj, At, Bt) do { __builtin_amdgcn_s_setprio(1); _Pragma("unroll") for (int m = 0; m < 4; ++m) _Pragma("unroll") for (int n = 0; n < 2; ++n) _Pragma("unroll") for (int k = 0; k < 2; ++k) \
;         acc[ai][bj][m][n] = __builtin_amdgcn_mfma_f32_16x16x32_bf16(Bt[n][k], At[m][k], acc[ai][bj][m][n], 0, 0, 0); __builtin_amdgcn_s_setprio(0); } while (0)
; #define PG8_WAIT_V(n) asm volatile("s_waitcnt vmcnt(" #n ")" ::: "memory")
; #define PG8_WAIT_L(n) asm volatile("s_waitcnt lgkmcnt(" #n ")" ::: "memory")
; #define PG8_BAR __builtin_amdgcn_s_barrier()
; #define PG8_SCHED __builtin_amdgcn_sched_barrier(0)
; template <class Epi, class Sched, bool ALIGN_EPI = false, bool SP2 = false>
; __device__ __forceinline__ void gemm_phase(PG8_LAS unsigned char* lds, const Gemm g, const Sched& S, const Epi& E, int tid_in) {
;     ...
;             PG8_LDA(At, 1, 1); PG8_STAGE(PG8_SB(1, 0), b3, voffB); PG8_STAGE(PG8_SB(1, 1), b3 + hstep, voffB); PG8_STAGE(PG8_SA(1, 0), a3, voffA);
;             PG8_WAIT_V(8); PG8_WAIT_L(0); PG8_BAR; PG8_MMA(1, 0, At, B0); PG8_MMA(1, 1, At, B1); PG8_BAR; PG8_SCHED;
;     ...
;         if constexpr (ALIGN_EPI) { if (wr == 0) PG8_BAR; }
	s_add_i32 s8, s58, s88
	v_lshl_add_u64 v[6:7], v[192:193], 0, s[96:97]
	s_mov_b32 m0, s8
	ds_read_b128 v[164:167], v208 offset:49152
	ds_read_b128 v[168:171], v208 offset:50176
	ds_read_b128 v[184:187], v208 offset:51200
	ds_read_b128 v[188:191], v208 offset:52224
	ds_read_b128 v[196:199], v208 offset:53248
	ds_read_b128 v[200:203], v208 offset:54272
	ds_read_b128 v[210:213], v208 offset:55296
	ds_read_b128 v[214:217], v208 offset:56320
	global_load_lds_dwordx4 v[6:7], off
	v_lshl_add_u64 v[6:7], v[204:205], 0, s[96:97]
	s_add_i32 m0, s8, 0x2000
	s_add_i32 s8, s59, s88
	global_load_lds_dwordx4 v[6:7], off
	v_lshl_add_u64 v[6:7], v[218:219], 0, s[96:97]
	s_mov_b32 m0, s8
	s_nop 0
	global_load_lds_dwordx4 v[6:7], off
	v_lshl_add_u64 v[6:7], v[220:221], 0, s[96:97]
	s_add_i32 m0, s8, 0x2000
	s_nop 0
	global_load_lds_dwordx4 v[6:7], off
	v_lshl_add_u64 v[6:7], s[0:1], 0, v[176:177]
	s_mov_b32 m0, s93
	s_nop 0
	global_load_lds_dwordx4 v[6:7], off
	v_lshl_add_u64 v[6:7], s[0:1], 0, v[172:173]
	s_mov_b32 m0, s78
	s_nop 0
	global_load_lds_dwordx4 v[6:7], off
	s_waitcnt vmcnt(8)
	s_waitcnt lgkmcnt(0)
	s_barrier
	s_setprio 2
	s_waitcnt lgkmcnt(0)
	v_mfma_f32_16x16x32_bf16 v[60:63], v[132:135], v[164:167], v[60:63]
	v_mfma_f32_16x16x32_bf16 v[52:55], v[140:143], v[164:167], v[52:55]
	v_mfma_f32_16x16x32_bf16 v[44:47], v[132:135], v[184:187], v[44:47]
	v_mfma_f32_16x16x32_bf16 v[36:39], v[140:143], v[184:187], v[36:39]
	v_mfma_f32_16x16x32_bf16 v[28:31], v[132:135], v[196:199], v[28:31]
	v_mfma_f32_16x16x32_bf16 v[20:23], v[140:143], v[196:199], v[20:23]
	v_mfma_f32_16x16x32_bf16 v[12:15], v[132:135], v[210:213], v[12:15]
	v_mfma_f32_16x16x32_bf16 v[2:5], v[140:143], v[210:213], v[2:5]
	v_mfma_f32_16x16x32_bf16 v[60:63], v[136:139], v[168:171], v[60:63]
	v_mfma_f32_16x16x32_bf16 v[52:55], v[144:147], v[168:171], v[52:55]
	v_mfma_f32_16x16x32_bf16 v[44:47], v[136:139], v[188:191], v[44:47]
	v_mfma_f32_16x16x32_bf16 v[36:39], v[144:147], v[188:191], v[36:39]
	v_mfma_f32_16x16x32_bf16 v[28:31], v[136:139], v[200:203], v[28:31]
	v_mfma_f32_16x16x32_bf16 v[20:23], v[144:147], v[200:203], v[20:23]
	v_mfma_f32_16x16x32_bf16 v[12:15], v[136:139], v[214:217], v[12:15]
	v_mfma_f32_16x16x32_bf16 v[4:7], v[144:147], v[214:217], v[2:5]
	s_setprio 1
	s_setprio 2
	v_mfma_f32_16x16x32_bf16 v[64:67], v[148:151], v[164:167], v[64:67]
	v_mfma_f32_16x16x32_bf16 v[56:59], v[156:159], v[164:167], v[56:59]
	v_mfma_f32_16x16x32_bf16 v[48:51], v[148:151], v[184:187], v[48:51]
	v_mfma_f32_16x16x32_bf16 v[40:43], v[156:159], v[184:187], v[40:43]
	v_mfma_f32_16x16x32_bf16 v[32:35], v[148:151], v[196:199], v[32:35]
	v_mfma_f32_16x16x32_bf16 v[24:27], v[156:159], v[196:199], v[24:27]
	v_mfma_f32_16x16x32_bf16 v[16:19], v[148:151], v[210:213], v[16:19]
	v_mfma_f32_16x16x32_bf16 v[8:11], v[156:159], v[210:213], v[8:11]
	v_mfma_f32_16x16x32_bf16 v[64:67], v[152:155], v[168:171], v[64:67]
	v_mfma_f32_16x16x32_bf16 v[56:59], v[160:163], v[168:171], v[56:59]
	v_mfma_f32_16x16x32_bf16 v[48:51], v[152:155], v[188:191], v[48:51]
	v_mfma_f32_16x16x32_bf16 v[40:43], v[160:163], v[188:191], v[40:43]
	v_mfma_f32_16x16x32_bf16 v[32:35], v[152:155], v[200:203], v[32:35]
	v_mfma_f32_16x16x32_bf16 v[24:27], v[160:163], v[200:203], v[24:27]
	v_mfma_f32_16x16x32_bf16 v[16:19], v[152:155], v[214:217], v[16:19]
	v_mfma_f32_16x16x32_bf16 v[8:11], v[160:163], v[214:217], v[8:11]
	s_setprio 1
	s_barrier
	s_add_u32 s6, s6, 0x100
	s_addc_u32 s7, s7, 0
	s_add_u32 s54, s54, 0x100
	s_addc_u32 s55, s55, 0
	s_add_i32 s56, s56, -2
	s_cmp_ge_u32 s57, s18
	s_mov_b32 s0, s57
	s_cbranch_scc0 .Lyk1_loop
	s_setprio 0
.Lyk1_exit:
	s_and_b64 vcc, exec, s[76:77]
	s_cbranch_vccz .LBB0_1183
	s_barrier
